# compress K loop unrolled 2-deep pipelined (36 loads in flight); top-k rank loops with one u64 compare per step; EpiResid/PV/bias edits
# speedup vs baseline: 1.0209x; 1.0047x over previous
; DI void prep_phase(const int wv, const Params& p, int l, LAS unsigned char* lds) {
;     ...
; #pragma unroll 2
;             for (int kk = 0; kk < 16; ++kk) { const int ks = 16 * wave + kk;
;                 const bf16x8 a = *(const bf16x8*)(Arow + (size_t)(ks >> 2) * PWID + (ks & 3) * 32);
; #pragma unroll
;                 for (int nt = 0; nt < 8; ++nt) { const bf16x8 bb = *(const bf16x8*)(Brow + (size_t)nt * 16 * 4096 + ks * 32);
;                     acc[nt] = __builtin_amdgcn_mfma_f32_16x16x32_bf16(a, bb, acc[nt], 0, 0, 0); }
;             }
.LBB0_362:
	s_sub_i32 s17, s1, 32
	v_ashrrev_i32_e32 v50, 2, v80
	s_and_b32 s17, s17, 64
	v_mad_i64_i32 v[50:51], s[18:19], v50, s68, v[46:47]
	s_lshl_b32 s86, s17, 1
	v_lshl_add_u64 v[50:51], v[50:51], 0, s[86:87]
	global_load_dwordx4 v[82:85], v[50:51], off
	v_add_u32_e32 v81, 1, v80
	v_ashrrev_i32_e32 v81, 2, v81
	s_and_b32 s17, s1, 0x60
	s_lshl_b32 s86, s17, 1
	v_mad_i64_i32 v[52:53], s[18:19], v81, s68, v[46:47]
	v_lshl_add_u64 v[52:53], v[52:53], 0, s[86:87]
	global_load_dwordx4 v[86:89], v[52:53], off
	v_add_u32_e32 v80, 2, v80
	v_lshl_add_u64 v[90:91], v[48:49], 0, s[12:13]
	s_mov_b32 s17, 0x5b00000
	v_add_co_u32_e32 v54, vcc, s17, v90
	s_mov_b32 s17, 0x5b20000
	s_nop 0
	v_addc_co_u32_e32 v55, vcc, 0, v91, vcc
	v_add_co_u32_e32 v56, vcc, s17, v90
	s_mov_b32 s17, 0x5b40000
	s_nop 0
	v_addc_co_u32_e32 v57, vcc, 0, v91, vcc
	v_add_co_u32_e32 v58, vcc, s17, v90
	s_mov_b32 s17, 0x5b60000
	s_nop 0
	v_addc_co_u32_e32 v59, vcc, 0, v91, vcc
	v_add_co_u32_e32 v60, vcc, s17, v90
	s_mov_b32 s17, 0x5b80000
	s_nop 0
	v_addc_co_u32_e32 v61, vcc, 0, v91, vcc
	v_add_co_u32_e32 v62, vcc, s17, v90
	s_mov_b32 s17, 0x5ba0000
	s_nop 0
	v_addc_co_u32_e32 v63, vcc, 0, v91, vcc
	v_add_co_u32_e32 v64, vcc, s17, v90
	s_mov_b32 s17, 0x5bc0000
	s_nop 0
	v_addc_co_u32_e32 v65, vcc, 0, v91, vcc
	v_add_co_u32_e32 v156, vcc, s17, v90
	s_mov_b32 s17, 0x5be0000
	s_nop 0
	v_addc_co_u32_e32 v157, vcc, 0, v91, vcc
	v_add_co_u32_e32 v158, vcc, s17, v90
	s_mov_b32 s17, 0x5c00000
	s_nop 0
	v_addc_co_u32_e32 v159, vcc, 0, v91, vcc
	global_load_dwordx4 v[92:95], v[54:55], off
	global_load_dwordx4 v[96:99], v[56:57], off
	global_load_dwordx4 v[100:103], v[58:59], off
	global_load_dwordx4 v[104:107], v[60:61], off
	global_load_dwordx4 v[108:111], v[62:63], off
	global_load_dwordx4 v[112:115], v[64:65], off
	global_load_dwordx4 v[116:119], v[156:157], off
	global_load_dwordx4 v[120:123], v[158:159], off
	global_load_dwordx4 v[124:127], v[54:55], off offset:64
	global_load_dwordx4 v[128:131], v[56:57], off offset:64
	global_load_dwordx4 v[132:135], v[58:59], off offset:64
	global_load_dwordx4 v[136:139], v[60:61], off offset:64
	global_load_dwordx4 v[140:143], v[62:63], off offset:64
	global_load_dwordx4 v[144:147], v[64:65], off offset:64
	global_load_dwordx4 v[148:151], v[156:157], off offset:64
	global_load_dwordx4 v[152:155], v[158:159], off offset:64
	s_add_u32 s12, s12, 0x80
	s_addc_u32 s13, s13, 0
	s_add_i32 s1, s1, 64
	s_sub_i32 s17, s1, 32
	v_ashrrev_i32_e32 v50, 2, v80
	s_and_b32 s17, s17, 64
	v_mad_i64_i32 v[50:51], s[18:19], v50, s68, v[46:47]
	s_lshl_b32 s86, s17, 1
	v_lshl_add_u64 v[50:51], v[50:51], 0, s[86:87]
	global_load_dwordx4 v[162:165], v[50:51], off
	v_add_u32_e32 v81, 1, v80
	v_ashrrev_i32_e32 v81, 2, v81
	s_and_b32 s17, s1, 0x60
	s_lshl_b32 s86, s17, 1
	v_mad_i64_i32 v[52:53], s[18:19], v81, s68, v[46:47]
	v_lshl_add_u64 v[52:53], v[52:53], 0, s[86:87]
	global_load_dwordx4 v[168:171], v[52:53], off
	v_add_u32_e32 v80, 2, v80
	v_lshl_add_u64 v[90:91], v[48:49], 0, s[12:13]
	s_mov_b32 s17, 0x5b00000
	v_add_co_u32_e32 v54, vcc, s17, v90
	s_mov_b32 s17, 0x5b20000
	s_nop 0
	v_addc_co_u32_e32 v55, vcc, 0, v91, vcc
	v_add_co_u32_e32 v56, vcc, s17, v90
	s_mov_b32 s17, 0x5b40000
	s_nop 0
	v_addc_co_u32_e32 v57, vcc, 0, v91, vcc
	v_add_co_u32_e32 v58, vcc, s17, v90
	s_mov_b32 s17, 0x5b60000
	s_nop 0
	v_addc_co_u32_e32 v59, vcc, 0, v91, vcc
	v_add_co_u32_e32 v60, vcc, s17, v90
	s_mov_b32 s17, 0x5b80000
	s_nop 0
	v_addc_co_u32_e32 v61, vcc, 0, v91, vcc
	v_add_co_u32_e32 v62, vcc, s17, v90
	s_mov_b32 s17, 0x5ba0000
	s_nop 0
	v_addc_co_u32_e32 v63, vcc, 0, v91, vcc
	v_add_co_u32_e32 v64, vcc, s17, v90
	s_mov_b32 s17, 0x5bc0000
	s_nop 0
	v_addc_co_u32_e32 v65, vcc, 0, v91, vcc
	v_add_co_u32_e32 v156, vcc, s17, v90
	s_mov_b32 s17, 0x5be0000
	s_nop 0
	v_addc_co_u32_e32 v157, vcc, 0, v91, vcc
	v_add_co_u32_e32 v158, vcc, s17, v90
	s_mov_b32 s17, 0x5c00000
	s_nop 0
	v_addc_co_u32_e32 v159, vcc, 0, v91, vcc
	global_load_dwordx4 v[172:175], v[54:55], off
	global_load_dwordx4 v[176:179], v[56:57], off
	global_load_dwordx4 v[180:183], v[58:59], off
	global_load_dwordx4 v[184:187], v[60:61], off
	global_load_dwordx4 v[188:191], v[62:63], off
	global_load_dwordx4 v[192:195], v[64:65], off
	global_load_dwordx4 v[196:199], v[156:157], off
	global_load_dwordx4 v[210:213], v[158:159], off
	global_load_dwordx4 v[214:217], v[54:55], off offset:64
	global_load_dwordx4 v[218:221], v[56:57], off offset:64
	global_load_dwordx4 v[222:225], v[58:59], off offset:64
	global_load_dwordx4 v[226:229], v[60:61], off offset:64
	global_load_dwordx4 v[230:233], v[62:63], off offset:64
	global_load_dwordx4 v[234:237], v[64:65], off offset:64
	global_load_dwordx4 v[238:241], v[156:157], off offset:64
	global_load_dwordx4 v[242:245], v[158:159], off offset:64
	s_add_u32 s12, s12, 0x80
	s_addc_u32 s13, s13, 0
	s_add_i32 s1, s1, 64
	s_waitcnt vmcnt(33)
	v_mfma_f32_16x16x32_bf16 v[16:19], v[82:85], v[92:95], v[16:19]
	s_waitcnt vmcnt(32)
	v_mfma_f32_16x16x32_bf16 v[20:23], v[82:85], v[96:99], v[20:23]
	s_waitcnt vmcnt(31)
	v_mfma_f32_16x16x32_bf16 v[12:15], v[82:85], v[100:103], v[12:15]
	s_waitcnt vmcnt(30)
	v_mfma_f32_16x16x32_bf16 v[8:11], v[82:85], v[104:107], v[8:11]
	s_waitcnt vmcnt(29)
	v_mfma_f32_16x16x32_bf16 v[24:27], v[82:85], v[108:111], v[24:27]
	s_waitcnt vmcnt(28)
	v_mfma_f32_16x16x32_bf16 v[28:31], v[82:85], v[112:115], v[28:31]
	s_waitcnt vmcnt(27)
	v_mfma_f32_16x16x32_bf16 v[0:3], v[82:85], v[116:119], v[0:3]
	s_waitcnt vmcnt(26)
	v_mfma_f32_16x16x32_bf16 v[4:7], v[82:85], v[120:123], v[4:7]
	s_waitcnt vmcnt(25)
	v_mfma_f32_16x16x32_bf16 v[16:19], v[86:89], v[124:127], v[16:19]
	s_waitcnt vmcnt(24)
; DI void prep_phase(const int wv, const Params& p, int l, LAS unsigned char* lds) {
;     ...
; #pragma unroll 2
;             for (int kk = 0; kk < 16; ++kk) { const int ks = 16 * wave + kk;
;                 const bf16x8 a = *(const bf16x8*)(Arow + (size_t)(ks >> 2) * PWID + (ks & 3) * 32);
; #pragma unroll
;                 for (int nt = 0; nt < 8; ++nt) { const bf16x8 bb = *(const bf16x8*)(Brow + (size_t)nt * 16 * 4096 + ks * 32);
;                     acc[nt] = __builtin_amdgcn_mfma_f32_16x16x32_bf16(a, bb, acc[nt], 0, 0, 0); }
;             }
	v_mfma_f32_16x16x32_bf16 v[20:23], v[86:89], v[128:131], v[20:23]
	s_waitcnt vmcnt(23)
	v_mfma_f32_16x16x32_bf16 v[12:15], v[86:89], v[132:135], v[12:15]
	s_waitcnt vmcnt(22)
	v_mfma_f32_16x16x32_bf16 v[8:11], v[86:89], v[136:139], v[8:11]
	s_waitcnt vmcnt(21)
	v_mfma_f32_16x16x32_bf16 v[24:27], v[86:89], v[140:143], v[24:27]
	s_waitcnt vmcnt(20)
	v_mfma_f32_16x16x32_bf16 v[28:31], v[86:89], v[144:147], v[28:31]
	s_waitcnt vmcnt(19)
	v_mfma_f32_16x16x32_bf16 v[0:3], v[86:89], v[148:151], v[0:3]
	s_waitcnt vmcnt(18)
	v_mfma_f32_16x16x32_bf16 v[4:7], v[86:89], v[152:155], v[4:7]
	s_sub_i32 s17, s1, 32
	v_ashrrev_i32_e32 v50, 2, v80
	s_and_b32 s17, s17, 64
	v_mad_i64_i32 v[50:51], s[18:19], v50, s68, v[46:47]
	s_lshl_b32 s86, s17, 1
	v_lshl_add_u64 v[50:51], v[50:51], 0, s[86:87]
	global_load_dwordx4 v[82:85], v[50:51], off
	v_add_u32_e32 v81, 1, v80
	v_ashrrev_i32_e32 v81, 2, v81
	s_and_b32 s17, s1, 0x60
	s_lshl_b32 s86, s17, 1
	v_mad_i64_i32 v[52:53], s[18:19], v81, s68, v[46:47]
	v_lshl_add_u64 v[52:53], v[52:53], 0, s[86:87]
	global_load_dwordx4 v[86:89], v[52:53], off
	v_add_u32_e32 v80, 2, v80
	v_lshl_add_u64 v[90:91], v[48:49], 0, s[12:13]
	s_mov_b32 s17, 0x5b00000
	v_add_co_u32_e32 v54, vcc, s17, v90
	s_mov_b32 s17, 0x5b20000
	s_nop 0
	v_addc_co_u32_e32 v55, vcc, 0, v91, vcc
	v_add_co_u32_e32 v56, vcc, s17, v90
	s_mov_b32 s17, 0x5b40000
	s_nop 0
	v_addc_co_u32_e32 v57, vcc, 0, v91, vcc
	v_add_co_u32_e32 v58, vcc, s17, v90
	s_mov_b32 s17, 0x5b60000
	s_nop 0
	v_addc_co_u32_e32 v59, vcc, 0, v91, vcc
	v_add_co_u32_e32 v60, vcc, s17, v90
	s_mov_b32 s17, 0x5b80000
	s_nop 0
	v_addc_co_u32_e32 v61, vcc, 0, v91, vcc
	v_add_co_u32_e32 v62, vcc, s17, v90
	s_mov_b32 s17, 0x5ba0000
	s_nop 0
	v_addc_co_u32_e32 v63, vcc, 0, v91, vcc
	v_add_co_u32_e32 v64, vcc, s17, v90
	s_mov_b32 s17, 0x5bc0000
	s_nop 0
	v_addc_co_u32_e32 v65, vcc, 0, v91, vcc
	v_add_co_u32_e32 v156, vcc, s17, v90
	s_mov_b32 s17, 0x5be0000
	s_nop 0
	v_addc_co_u32_e32 v157, vcc, 0, v91, vcc
	v_add_co_u32_e32 v158, vcc, s17, v90
	s_mov_b32 s17, 0x5c00000
	s_nop 0
	v_addc_co_u32_e32 v159, vcc, 0, v91, vcc
	global_load_dwordx4 v[92:95], v[54:55], off
	global_load_dwordx4 v[96:99], v[56:57], off
	global_load_dwordx4 v[100:103], v[58:59], off
	global_load_dwordx4 v[104:107], v[60:61], off
	global_load_dwordx4 v[108:111], v[62:63], off
	global_load_dwordx4 v[112:115], v[64:65], off
	global_load_dwordx4 v[116:119], v[156:157], off
	global_load_dwordx4 v[120:123], v[158:159], off
	global_load_dwordx4 v[124:127], v[54:55], off offset:64
	global_load_dwordx4 v[128:131], v[56:57], off offset:64
	global_load_dwordx4 v[132:135], v[58:59], off offset:64
	global_load_dwordx4 v[136:139], v[60:61], off offset:64
	global_load_dwordx4 v[140:143], v[62:63], off offset:64
	global_load_dwordx4 v[144:147], v[64:65], off offset:64
	global_load_dwordx4 v[148:151], v[156:157], off offset:64
	global_load_dwordx4 v[152:155], v[158:159], off offset:64
	s_add_u32 s12, s12, 0x80
	s_addc_u32 s13, s13, 0
	s_add_i32 s1, s1, 64
	s_waitcnt vmcnt(33)
	v_mfma_f32_16x16x32_bf16 v[16:19], v[162:165], v[172:175], v[16:19]
	s_waitcnt vmcnt(32)
	v_mfma_f32_16x16x32_bf16 v[20:23], v[162:165], v[176:179], v[20:23]
	s_waitcnt vmcnt(31)
	v_mfma_f32_16x16x32_bf16 v[12:15], v[162:165], v[180:183], v[12:15]
	s_waitcnt vmcnt(30)
	v_mfma_f32_16x16x32_bf16 v[8:11], v[162:165], v[184:187], v[8:11]
	s_waitcnt vmcnt(29)
	v_mfma_f32_16x16x32_bf16 v[24:27], v[162:165], v[188:191], v[24:27]
	s_waitcnt vmcnt(28)
	v_mfma_f32_16x16x32_bf16 v[28:31], v[162:165], v[192:195], v[28:31]
	s_waitcnt vmcnt(27)
	v_mfma_f32_16x16x32_bf16 v[0:3], v[162:165], v[196:199], v[0:3]
	s_waitcnt vmcnt(26)
	v_mfma_f32_16x16x32_bf16 v[4:7], v[162:165], v[210:213], v[4:7]
	s_waitcnt vmcnt(25)
	v_mfma_f32_16x16x32_bf16 v[16:19], v[168:171], v[214:217], v[16:19]
	s_waitcnt vmcnt(24)
	v_mfma_f32_16x16x32_bf16 v[20:23], v[168:171], v[218:221], v[20:23]
	s_waitcnt vmcnt(23)
	v_mfma_f32_16x16x32_bf16 v[12:15], v[168:171], v[222:225], v[12:15]
	s_waitcnt vmcnt(22)
	v_mfma_f32_16x16x32_bf16 v[8:11], v[168:171], v[226:229], v[8:11]
	s_waitcnt vmcnt(21)
	v_mfma_f32_16x16x32_bf16 v[24:27], v[168:171], v[230:233], v[24:27]
	s_waitcnt vmcnt(20)
	v_mfma_f32_16x16x32_bf16 v[28:31], v[168:171], v[234:237], v[28:31]
	s_waitcnt vmcnt(19)
	v_mfma_f32_16x16x32_bf16 v[0:3], v[168:171], v[238:241], v[0:3]
	s_waitcnt vmcnt(18)
	v_mfma_f32_16x16x32_bf16 v[4:7], v[168:171], v[242:245], v[4:7]
	s_sub_i32 s17, s1, 32
	v_ashrrev_i32_e32 v50, 2, v80
	s_and_b32 s17, s17, 64
	v_mad_i64_i32 v[50:51], s[18:19], v50, s68, v[46:47]
	s_lshl_b32 s86, s17, 1
	v_lshl_add_u64 v[50:51], v[50:51], 0, s[86:87]
	global_load_dwordx4 v[162:165], v[50:51], off
	v_add_u32_e32 v81, 1, v80
	v_ashrrev_i32_e32 v81, 2, v81
	s_and_b32 s17, s1, 0x60
	s_lshl_b32 s86, s17, 1
	v_mad_i64_i32 v[52:53], s[18:19], v81, s68, v[46:47]
	v_lshl_add_u64 v[52:53], v[52:53], 0, s[86:87]
	global_load_dwordx4 v[168:171], v[52:53], off
	v_add_u32_e32 v80, 2, v80
	v_lshl_add_u64 v[90:91], v[48:49], 0, s[12:13]
	s_mov_b32 s17, 0x5b00000
	v_add_co_u32_e32 v54, vcc, s17, v90
	s_mov_b32 s17, 0x5b20000
	s_nop 0
	v_addc_co_u32_e32 v55, vcc, 0, v91, vcc
	v_add_co_u32_e32 v56, vcc, s17, v90
	s_mov_b32 s17, 0x5b40000
	s_nop 0
	v_addc_co_u32_e32 v57, vcc, 0, v91, vcc
	v_add_co_u32_e32 v58, vcc, s17, v90
	s_mov_b32 s17, 0x5b60000
	s_nop 0
	v_addc_co_u32_e32 v59, vcc, 0, v91, vcc
	v_add_co_u32_e32 v60, vcc, s17, v90
	s_mov_b32 s17, 0x5b80000
	s_nop 0
	v_addc_co_u32_e32 v61, vcc, 0, v91, vcc
	v_add_co_u32_e32 v62, vcc, s17, v90
	s_mov_b32 s17, 0x5ba0000
	s_nop 0
	v_addc_co_u32_e32 v63, vcc, 0, v91, vcc
	v_add_co_u32_e32 v64, vcc, s17, v90
	s_mov_b32 s17, 0x5bc0000
	s_nop 0
	v_addc_co_u32_e32 v65, vcc, 0, v91, vcc
	v_add_co_u32_e32 v156, vcc, s17, v90
	s_mov_b32 s17, 0x5be0000
	s_nop 0
	v_addc_co_u32_e32 v157, vcc, 0, v91, vcc
	v_add_co_u32_e32 v158, vcc, s17, v90
	s_mov_b32 s17, 0x5c00000
	s_nop 0
	v_addc_co_u32_e32 v159, vcc, 0, v91, vcc
	global_load_dwordx4 v[172:175], v[54:55], off
	global_load_dwordx4 v[176:179], v[56:57], off
	global_load_dwordx4 v[180:183], v[58:59], off
	global_load_dwordx4 v[184:187], v[60:61], off
	global_load_dwordx4 v[188:191], v[62:63], off
	global_load_dwordx4 v[192:195], v[64:65], off
	global_load_dwordx4 v[196:199], v[156:157], off
	global_load_dwordx4 v[210:213], v[158:159], off
	global_load_dwordx4 v[214:217], v[54:55], off offset:64
	global_load_dwordx4 v[218:221], v[56:57], off offset:64
	global_load_dwordx4 v[222:225], v[58:59], off offset:64
	global_load_dwordx4 v[226:229], v[60:61], off offset:64
	global_load_dwordx4 v[230:233], v[62:63], off offset:64
	global_load_dwordx4 v[234:237], v[64:65], off offset:64
	global_load_dwordx4 v[238:241], v[156:157], off offset:64
	global_load_dwordx4 v[242:245], v[158:159], off offset:64
	s_add_u32 s12, s12, 0x80
	s_addc_u32 s13, s13, 0
	s_add_i32 s1, s1, 64
	s_waitcnt vmcnt(33)
; DI void prep_phase(const int wv, const Params& p, int l, LAS unsigned char* lds) {
;     ...
; #pragma unroll 2
;             for (int kk = 0; kk < 16; ++kk) { const int ks = 16 * wave + kk;
;                 const bf16x8 a = *(const bf16x8*)(Arow + (size_t)(ks >> 2) * PWID + (ks & 3) * 32);
; #pragma unroll
;                 for (int nt = 0; nt < 8; ++nt) { const bf16x8 bb = *(const bf16x8*)(Brow + (size_t)nt * 16 * 4096 + ks * 32);
;                     acc[nt] = __builtin_amdgcn_mfma_f32_16x16x32_bf16(a, bb, acc[nt], 0, 0, 0); }
;             }
	v_mfma_f32_16x16x32_bf16 v[16:19], v[82:85], v[92:95], v[16:19]
	s_waitcnt vmcnt(32)
	v_mfma_f32_16x16x32_bf16 v[20:23], v[82:85], v[96:99], v[20:23]
	s_waitcnt vmcnt(31)
	v_mfma_f32_16x16x32_bf16 v[12:15], v[82:85], v[100:103], v[12:15]
	s_waitcnt vmcnt(30)
	v_mfma_f32_16x16x32_bf16 v[8:11], v[82:85], v[104:107], v[8:11]
	s_waitcnt vmcnt(29)
	v_mfma_f32_16x16x32_bf16 v[24:27], v[82:85], v[108:111], v[24:27]
	s_waitcnt vmcnt(28)
	v_mfma_f32_16x16x32_bf16 v[28:31], v[82:85], v[112:115], v[28:31]
	s_waitcnt vmcnt(27)
	v_mfma_f32_16x16x32_bf16 v[0:3], v[82:85], v[116:119], v[0:3]
	s_waitcnt vmcnt(26)
	v_mfma_f32_16x16x32_bf16 v[4:7], v[82:85], v[120:123], v[4:7]
	s_waitcnt vmcnt(25)
	v_mfma_f32_16x16x32_bf16 v[16:19], v[86:89], v[124:127], v[16:19]
	s_waitcnt vmcnt(24)
	v_mfma_f32_16x16x32_bf16 v[20:23], v[86:89], v[128:131], v[20:23]
	s_waitcnt vmcnt(23)
	v_mfma_f32_16x16x32_bf16 v[12:15], v[86:89], v[132:135], v[12:15]
	s_waitcnt vmcnt(22)
	v_mfma_f32_16x16x32_bf16 v[8:11], v[86:89], v[136:139], v[8:11]
	s_waitcnt vmcnt(21)
	v_mfma_f32_16x16x32_bf16 v[24:27], v[86:89], v[140:143], v[24:27]
	s_waitcnt vmcnt(20)
	v_mfma_f32_16x16x32_bf16 v[28:31], v[86:89], v[144:147], v[28:31]
	s_waitcnt vmcnt(19)
	v_mfma_f32_16x16x32_bf16 v[0:3], v[86:89], v[148:151], v[0:3]
	s_waitcnt vmcnt(18)
	v_mfma_f32_16x16x32_bf16 v[4:7], v[86:89], v[152:155], v[4:7]
	s_sub_i32 s17, s1, 32
	v_ashrrev_i32_e32 v50, 2, v80
	s_and_b32 s17, s17, 64
	v_mad_i64_i32 v[50:51], s[18:19], v50, s68, v[46:47]
	s_lshl_b32 s86, s17, 1
	v_lshl_add_u64 v[50:51], v[50:51], 0, s[86:87]
	global_load_dwordx4 v[82:85], v[50:51], off
	v_add_u32_e32 v81, 1, v80
	v_ashrrev_i32_e32 v81, 2, v81
	s_and_b32 s17, s1, 0x60
	s_lshl_b32 s86, s17, 1
	v_mad_i64_i32 v[52:53], s[18:19], v81, s68, v[46:47]
	v_lshl_add_u64 v[52:53], v[52:53], 0, s[86:87]
	global_load_dwordx4 v[86:89], v[52:53], off
	v_add_u32_e32 v80, 2, v80
	v_lshl_add_u64 v[90:91], v[48:49], 0, s[12:13]
	s_mov_b32 s17, 0x5b00000
	v_add_co_u32_e32 v54, vcc, s17, v90
	s_mov_b32 s17, 0x5b20000
	s_nop 0
	v_addc_co_u32_e32 v55, vcc, 0, v91, vcc
	v_add_co_u32_e32 v56, vcc, s17, v90
	s_mov_b32 s17, 0x5b40000
	s_nop 0
	v_addc_co_u32_e32 v57, vcc, 0, v91, vcc
	v_add_co_u32_e32 v58, vcc, s17, v90
	s_mov_b32 s17, 0x5b60000
	s_nop 0
	v_addc_co_u32_e32 v59, vcc, 0, v91, vcc
	v_add_co_u32_e32 v60, vcc, s17, v90
	s_mov_b32 s17, 0x5b80000
	s_nop 0
	v_addc_co_u32_e32 v61, vcc, 0, v91, vcc
	v_add_co_u32_e32 v62, vcc, s17, v90
	s_mov_b32 s17, 0x5ba0000
	s_nop 0
	v_addc_co_u32_e32 v63, vcc, 0, v91, vcc
	v_add_co_u32_e32 v64, vcc, s17, v90
	s_mov_b32 s17, 0x5bc0000
	s_nop 0
	v_addc_co_u32_e32 v65, vcc, 0, v91, vcc
	v_add_co_u32_e32 v156, vcc, s17, v90
	s_mov_b32 s17, 0x5be0000
	s_nop 0
	v_addc_co_u32_e32 v157, vcc, 0, v91, vcc
	v_add_co_u32_e32 v158, vcc, s17, v90
	s_mov_b32 s17, 0x5c00000
	s_nop 0
	v_addc_co_u32_e32 v159, vcc, 0, v91, vcc
	global_load_dwordx4 v[92:95], v[54:55], off
	global_load_dwordx4 v[96:99], v[56:57], off
	global_load_dwordx4 v[100:103], v[58:59], off
	global_load_dwordx4 v[104:107], v[60:61], off
	global_load_dwordx4 v[108:111], v[62:63], off
	global_load_dwordx4 v[112:115], v[64:65], off
	global_load_dwordx4 v[116:119], v[156:157], off
	global_load_dwordx4 v[120:123], v[158:159], off
	global_load_dwordx4 v[124:127], v[54:55], off offset:64
	global_load_dwordx4 v[128:131], v[56:57], off offset:64
	global_load_dwordx4 v[132:135], v[58:59], off offset:64
	global_load_dwordx4 v[136:139], v[60:61], off offset:64
	global_load_dwordx4 v[140:143], v[62:63], off offset:64
	global_load_dwordx4 v[144:147], v[64:65], off offset:64
	global_load_dwordx4 v[148:151], v[156:157], off offset:64
	global_load_dwordx4 v[152:155], v[158:159], off offset:64
	s_add_u32 s12, s12, 0x80
	s_addc_u32 s13, s13, 0
	s_add_i32 s1, s1, 64
	s_waitcnt vmcnt(33)
	v_mfma_f32_16x16x32_bf16 v[16:19], v[162:165], v[172:175], v[16:19]
	s_waitcnt vmcnt(32)
	v_mfma_f32_16x16x32_bf16 v[20:23], v[162:165], v[176:179], v[20:23]
	s_waitcnt vmcnt(31)
	v_mfma_f32_16x16x32_bf16 v[12:15], v[162:165], v[180:183], v[12:15]
	s_waitcnt vmcnt(30)
	v_mfma_f32_16x16x32_bf16 v[8:11], v[162:165], v[184:187], v[8:11]
	s_waitcnt vmcnt(29)
	v_mfma_f32_16x16x32_bf16 v[24:27], v[162:165], v[188:191], v[24:27]
	s_waitcnt vmcnt(28)
	v_mfma_f32_16x16x32_bf16 v[28:31], v[162:165], v[192:195], v[28:31]
	s_waitcnt vmcnt(27)
	v_mfma_f32_16x16x32_bf16 v[0:3], v[162:165], v[196:199], v[0:3]
	s_waitcnt vmcnt(26)
	v_mfma_f32_16x16x32_bf16 v[4:7], v[162:165], v[210:213], v[4:7]
	s_waitcnt vmcnt(25)
	v_mfma_f32_16x16x32_bf16 v[16:19], v[168:171], v[214:217], v[16:19]
	s_waitcnt vmcnt(24)
	v_mfma_f32_16x16x32_bf16 v[20:23], v[168:171], v[218:221], v[20:23]
	s_waitcnt vmcnt(23)
	v_mfma_f32_16x16x32_bf16 v[12:15], v[168:171], v[222:225], v[12:15]
	s_waitcnt vmcnt(22)
	v_mfma_f32_16x16x32_bf16 v[8:11], v[168:171], v[226:229], v[8:11]
	s_waitcnt vmcnt(21)
	v_mfma_f32_16x16x32_bf16 v[24:27], v[168:171], v[230:233], v[24:27]
	s_waitcnt vmcnt(20)
	v_mfma_f32_16x16x32_bf16 v[28:31], v[168:171], v[234:237], v[28:31]
	s_waitcnt vmcnt(19)
	v_mfma_f32_16x16x32_bf16 v[0:3], v[168:171], v[238:241], v[0:3]
	s_waitcnt vmcnt(18)
; DI void prep_phase(const int wv, const Params& p, int l, LAS unsigned char* lds) {
;     ...
; #pragma unroll 2
;             for (int kk = 0; kk < 16; ++kk) { const int ks = 16 * wave + kk;
;                 const bf16x8 a = *(const bf16x8*)(Arow + (size_t)(ks >> 2) * PWID + (ks & 3) * 32);
; #pragma unroll
;                 for (int nt = 0; nt < 8; ++nt) { const bf16x8 bb = *(const bf16x8*)(Brow + (size_t)nt * 16 * 4096 + ks * 32);
;                     acc[nt] = __builtin_amdgcn_mfma_f32_16x16x32_bf16(a, bb, acc[nt], 0, 0, 0); }
;             }
	v_mfma_f32_16x16x32_bf16 v[4:7], v[168:171], v[242:245], v[4:7]
	s_sub_i32 s17, s1, 32
	v_ashrrev_i32_e32 v50, 2, v80
	s_and_b32 s17, s17, 64
	v_mad_i64_i32 v[50:51], s[18:19], v50, s68, v[46:47]
	s_lshl_b32 s86, s17, 1
	v_lshl_add_u64 v[50:51], v[50:51], 0, s[86:87]
	global_load_dwordx4 v[162:165], v[50:51], off
	v_add_u32_e32 v81, 1, v80
	v_ashrrev_i32_e32 v81, 2, v81
	s_and_b32 s17, s1, 0x60
	s_lshl_b32 s86, s17, 1
	v_mad_i64_i32 v[52:53], s[18:19], v81, s68, v[46:47]
	v_lshl_add_u64 v[52:53], v[52:53], 0, s[86:87]
	global_load_dwordx4 v[168:171], v[52:53], off
	v_add_u32_e32 v80, 2, v80
	v_lshl_add_u64 v[90:91], v[48:49], 0, s[12:13]
	s_mov_b32 s17, 0x5b00000
	v_add_co_u32_e32 v54, vcc, s17, v90
	s_mov_b32 s17, 0x5b20000
	s_nop 0
	v_addc_co_u32_e32 v55, vcc, 0, v91, vcc
	v_add_co_u32_e32 v56, vcc, s17, v90
	s_mov_b32 s17, 0x5b40000
	s_nop 0
	v_addc_co_u32_e32 v57, vcc, 0, v91, vcc
	v_add_co_u32_e32 v58, vcc, s17, v90
	s_mov_b32 s17, 0x5b60000
	s_nop 0
	v_addc_co_u32_e32 v59, vcc, 0, v91, vcc
	v_add_co_u32_e32 v60, vcc, s17, v90
	s_mov_b32 s17, 0x5b80000
	s_nop 0
	v_addc_co_u32_e32 v61, vcc, 0, v91, vcc
	v_add_co_u32_e32 v62, vcc, s17, v90
	s_mov_b32 s17, 0x5ba0000
	s_nop 0
	v_addc_co_u32_e32 v63, vcc, 0, v91, vcc
	v_add_co_u32_e32 v64, vcc, s17, v90
	s_mov_b32 s17, 0x5bc0000
	s_nop 0
	v_addc_co_u32_e32 v65, vcc, 0, v91, vcc
	v_add_co_u32_e32 v156, vcc, s17, v90
	s_mov_b32 s17, 0x5be0000
	s_nop 0
	v_addc_co_u32_e32 v157, vcc, 0, v91, vcc
	v_add_co_u32_e32 v158, vcc, s17, v90
	s_mov_b32 s17, 0x5c00000
	s_nop 0
	v_addc_co_u32_e32 v159, vcc, 0, v91, vcc
	global_load_dwordx4 v[172:175], v[54:55], off
	global_load_dwordx4 v[176:179], v[56:57], off
	global_load_dwordx4 v[180:183], v[58:59], off
	global_load_dwordx4 v[184:187], v[60:61], off
	global_load_dwordx4 v[188:191], v[62:63], off
	global_load_dwordx4 v[192:195], v[64:65], off
	global_load_dwordx4 v[196:199], v[156:157], off
	global_load_dwordx4 v[210:213], v[158:159], off
	global_load_dwordx4 v[214:217], v[54:55], off offset:64
	global_load_dwordx4 v[218:221], v[56:57], off offset:64
	global_load_dwordx4 v[222:225], v[58:59], off offset:64
	global_load_dwordx4 v[226:229], v[60:61], off offset:64
	global_load_dwordx4 v[230:233], v[62:63], off offset:64
	global_load_dwordx4 v[234:237], v[64:65], off offset:64
	global_load_dwordx4 v[238:241], v[156:157], off offset:64
	global_load_dwordx4 v[242:245], v[158:159], off offset:64
	s_add_u32 s12, s12, 0x80
	s_addc_u32 s13, s13, 0
	s_add_i32 s1, s1, 64
	s_waitcnt vmcnt(33)
	v_mfma_f32_16x16x32_bf16 v[16:19], v[82:85], v[92:95], v[16:19]
	s_waitcnt vmcnt(32)
	v_mfma_f32_16x16x32_bf16 v[20:23], v[82:85], v[96:99], v[20:23]
	s_waitcnt vmcnt(31)
	v_mfma_f32_16x16x32_bf16 v[12:15], v[82:85], v[100:103], v[12:15]
	s_waitcnt vmcnt(30)
	v_mfma_f32_16x16x32_bf16 v[8:11], v[82:85], v[104:107], v[8:11]
	s_waitcnt vmcnt(29)
	v_mfma_f32_16x16x32_bf16 v[24:27], v[82:85], v[108:111], v[24:27]
	s_waitcnt vmcnt(28)
	v_mfma_f32_16x16x32_bf16 v[28:31], v[82:85], v[112:115], v[28:31]
	s_waitcnt vmcnt(27)
	v_mfma_f32_16x16x32_bf16 v[0:3], v[82:85], v[116:119], v[0:3]
	s_waitcnt vmcnt(26)
	v_mfma_f32_16x16x32_bf16 v[4:7], v[82:85], v[120:123], v[4:7]
	s_waitcnt vmcnt(25)
	v_mfma_f32_16x16x32_bf16 v[16:19], v[86:89], v[124:127], v[16:19]
	s_waitcnt vmcnt(24)
	v_mfma_f32_16x16x32_bf16 v[20:23], v[86:89], v[128:131], v[20:23]
	s_waitcnt vmcnt(23)
	v_mfma_f32_16x16x32_bf16 v[12:15], v[86:89], v[132:135], v[12:15]
	s_waitcnt vmcnt(22)
	v_mfma_f32_16x16x32_bf16 v[8:11], v[86:89], v[136:139], v[8:11]
	s_waitcnt vmcnt(21)
	v_mfma_f32_16x16x32_bf16 v[24:27], v[86:89], v[140:143], v[24:27]
	s_waitcnt vmcnt(20)
	v_mfma_f32_16x16x32_bf16 v[28:31], v[86:89], v[144:147], v[28:31]
	s_waitcnt vmcnt(19)
	v_mfma_f32_16x16x32_bf16 v[0:3], v[86:89], v[148:151], v[0:3]
	s_waitcnt vmcnt(18)
	v_mfma_f32_16x16x32_bf16 v[4:7], v[86:89], v[152:155], v[4:7]
	s_sub_i32 s17, s1, 32
	v_ashrrev_i32_e32 v50, 2, v80
	s_and_b32 s17, s17, 64
	v_mad_i64_i32 v[50:51], s[18:19], v50, s68, v[46:47]
	s_lshl_b32 s86, s17, 1
	v_lshl_add_u64 v[50:51], v[50:51], 0, s[86:87]
	global_load_dwordx4 v[82:85], v[50:51], off
	v_add_u32_e32 v81, 1, v80
	v_ashrrev_i32_e32 v81, 2, v81
	s_and_b32 s17, s1, 0x60
	s_lshl_b32 s86, s17, 1
	v_mad_i64_i32 v[52:53], s[18:19], v81, s68, v[46:47]
	v_lshl_add_u64 v[52:53], v[52:53], 0, s[86:87]
	global_load_dwordx4 v[86:89], v[52:53], off
	v_add_u32_e32 v80, 2, v80
	v_lshl_add_u64 v[90:91], v[48:49], 0, s[12:13]
	s_mov_b32 s17, 0x5b00000
	v_add_co_u32_e32 v54, vcc, s17, v90
	s_mov_b32 s17, 0x5b20000
	s_nop 0
	v_addc_co_u32_e32 v55, vcc, 0, v91, vcc
	v_add_co_u32_e32 v56, vcc, s17, v90
	s_mov_b32 s17, 0x5b40000
	s_nop 0
	v_addc_co_u32_e32 v57, vcc, 0, v91, vcc
	v_add_co_u32_e32 v58, vcc, s17, v90
	s_mov_b32 s17, 0x5b60000
	s_nop 0
	v_addc_co_u32_e32 v59, vcc, 0, v91, vcc
	v_add_co_u32_e32 v60, vcc, s17, v90
	s_mov_b32 s17, 0x5b80000
	s_nop 0
	v_addc_co_u32_e32 v61, vcc, 0, v91, vcc
	v_add_co_u32_e32 v62, vcc, s17, v90
	s_mov_b32 s17, 0x5ba0000
	s_nop 0
	v_addc_co_u32_e32 v63, vcc, 0, v91, vcc
	v_add_co_u32_e32 v64, vcc, s17, v90
	s_mov_b32 s17, 0x5bc0000
	s_nop 0
	v_addc_co_u32_e32 v65, vcc, 0, v91, vcc
	v_add_co_u32_e32 v156, vcc, s17, v90
	s_mov_b32 s17, 0x5be0000
	s_nop 0
	v_addc_co_u32_e32 v157, vcc, 0, v91, vcc
	v_add_co_u32_e32 v158, vcc, s17, v90
	s_mov_b32 s17, 0x5c00000
	s_nop 0
	v_addc_co_u32_e32 v159, vcc, 0, v91, vcc
	global_load_dwordx4 v[92:95], v[54:55], off
	global_load_dwordx4 v[96:99], v[56:57], off
	global_load_dwordx4 v[100:103], v[58:59], off
	global_load_dwordx4 v[104:107], v[60:61], off
	global_load_dwordx4 v[108:111], v[62:63], off
	global_load_dwordx4 v[112:115], v[64:65], off
	global_load_dwordx4 v[116:119], v[156:157], off
	global_load_dwordx4 v[120:123], v[158:159], off
	global_load_dwordx4 v[124:127], v[54:55], off offset:64
	global_load_dwordx4 v[128:131], v[56:57], off offset:64
	global_load_dwordx4 v[132:135], v[58:59], off offset:64
	global_load_dwordx4 v[136:139], v[60:61], off offset:64
	global_load_dwordx4 v[140:143], v[62:63], off offset:64
	global_load_dwordx4 v[144:147], v[64:65], off offset:64
	global_load_dwordx4 v[148:151], v[156:157], off offset:64
	global_load_dwordx4 v[152:155], v[158:159], off offset:64
	s_add_u32 s12, s12, 0x80
	s_addc_u32 s13, s13, 0
	s_add_i32 s1, s1, 64
	s_waitcnt vmcnt(33)
; DI void prep_phase(const int wv, const Params& p, int l, LAS unsigned char* lds) {
;     ...
; #pragma unroll 2
;             for (int kk = 0; kk < 16; ++kk) { const int ks = 16 * wave + kk;
;                 const bf16x8 a = *(const bf16x8*)(Arow + (size_t)(ks >> 2) * PWID + (ks & 3) * 32);
; #pragma unroll
;                 for (int nt = 0; nt < 8; ++nt) { const bf16x8 bb = *(const bf16x8*)(Brow + (size_t)nt * 16 * 4096 + ks * 32);
;                     acc[nt] = __builtin_amdgcn_mfma_f32_16x16x32_bf16(a, bb, acc[nt], 0, 0, 0); }
;             }
	v_mfma_f32_16x16x32_bf16 v[16:19], v[162:165], v[172:175], v[16:19]
	s_waitcnt vmcnt(32)
	v_mfma_f32_16x16x32_bf16 v[20:23], v[162:165], v[176:179], v[20:23]
	s_waitcnt vmcnt(31)
	v_mfma_f32_16x16x32_bf16 v[12:15], v[162:165], v[180:183], v[12:15]
	s_waitcnt vmcnt(30)
	v_mfma_f32_16x16x32_bf16 v[8:11], v[162:165], v[184:187], v[8:11]
	s_waitcnt vmcnt(29)
	v_mfma_f32_16x16x32_bf16 v[24:27], v[162:165], v[188:191], v[24:27]
	s_waitcnt vmcnt(28)
	v_mfma_f32_16x16x32_bf16 v[28:31], v[162:165], v[192:195], v[28:31]
	s_waitcnt vmcnt(27)
	v_mfma_f32_16x16x32_bf16 v[0:3], v[162:165], v[196:199], v[0:3]
	s_waitcnt vmcnt(26)
	v_mfma_f32_16x16x32_bf16 v[4:7], v[162:165], v[210:213], v[4:7]
	s_waitcnt vmcnt(25)
	v_mfma_f32_16x16x32_bf16 v[16:19], v[168:171], v[214:217], v[16:19]
	s_waitcnt vmcnt(24)
	v_mfma_f32_16x16x32_bf16 v[20:23], v[168:171], v[218:221], v[20:23]
	s_waitcnt vmcnt(23)
	v_mfma_f32_16x16x32_bf16 v[12:15], v[168:171], v[222:225], v[12:15]
	s_waitcnt vmcnt(22)
	v_mfma_f32_16x16x32_bf16 v[8:11], v[168:171], v[226:229], v[8:11]
	s_waitcnt vmcnt(21)
	v_mfma_f32_16x16x32_bf16 v[24:27], v[168:171], v[230:233], v[24:27]
	s_waitcnt vmcnt(20)
	v_mfma_f32_16x16x32_bf16 v[28:31], v[168:171], v[234:237], v[28:31]
	s_waitcnt vmcnt(19)
	v_mfma_f32_16x16x32_bf16 v[0:3], v[168:171], v[238:241], v[0:3]
	s_waitcnt vmcnt(18)
	v_mfma_f32_16x16x32_bf16 v[4:7], v[168:171], v[242:245], v[4:7]
	s_sub_i32 s17, s1, 32
	v_ashrrev_i32_e32 v50, 2, v80
	s_and_b32 s17, s17, 64
	v_mad_i64_i32 v[50:51], s[18:19], v50, s68, v[46:47]
	s_lshl_b32 s86, s17, 1
	v_lshl_add_u64 v[50:51], v[50:51], 0, s[86:87]
	global_load_dwordx4 v[162:165], v[50:51], off
	v_add_u32_e32 v81, 1, v80
	v_ashrrev_i32_e32 v81, 2, v81
	s_and_b32 s17, s1, 0x60
	s_lshl_b32 s86, s17, 1
	v_mad_i64_i32 v[52:53], s[18:19], v81, s68, v[46:47]
	v_lshl_add_u64 v[52:53], v[52:53], 0, s[86:87]
	global_load_dwordx4 v[168:171], v[52:53], off
	v_add_u32_e32 v80, 2, v80
	v_lshl_add_u64 v[90:91], v[48:49], 0, s[12:13]
	s_mov_b32 s17, 0x5b00000
	v_add_co_u32_e32 v54, vcc, s17, v90
	s_mov_b32 s17, 0x5b20000
	s_nop 0
	v_addc_co_u32_e32 v55, vcc, 0, v91, vcc
	v_add_co_u32_e32 v56, vcc, s17, v90
	s_mov_b32 s17, 0x5b40000
	s_nop 0
	v_addc_co_u32_e32 v57, vcc, 0, v91, vcc
	v_add_co_u32_e32 v58, vcc, s17, v90
	s_mov_b32 s17, 0x5b60000
	s_nop 0
	v_addc_co_u32_e32 v59, vcc, 0, v91, vcc
	v_add_co_u32_e32 v60, vcc, s17, v90
	s_mov_b32 s17, 0x5b80000
	s_nop 0
	v_addc_co_u32_e32 v61, vcc, 0, v91, vcc
	v_add_co_u32_e32 v62, vcc, s17, v90
	s_mov_b32 s17, 0x5ba0000
	s_nop 0
	v_addc_co_u32_e32 v63, vcc, 0, v91, vcc
	v_add_co_u32_e32 v64, vcc, s17, v90
	s_mov_b32 s17, 0x5bc0000
	s_nop 0
	v_addc_co_u32_e32 v65, vcc, 0, v91, vcc
	v_add_co_u32_e32 v156, vcc, s17, v90
	s_mov_b32 s17, 0x5be0000
	s_nop 0
	v_addc_co_u32_e32 v157, vcc, 0, v91, vcc
	v_add_co_u32_e32 v158, vcc, s17, v90
	s_mov_b32 s17, 0x5c00000
	s_nop 0
	v_addc_co_u32_e32 v159, vcc, 0, v91, vcc
	global_load_dwordx4 v[172:175], v[54:55], off
	global_load_dwordx4 v[176:179], v[56:57], off
	global_load_dwordx4 v[180:183], v[58:59], off
	global_load_dwordx4 v[184:187], v[60:61], off
	global_load_dwordx4 v[188:191], v[62:63], off
	global_load_dwordx4 v[192:195], v[64:65], off
	global_load_dwordx4 v[196:199], v[156:157], off
	global_load_dwordx4 v[210:213], v[158:159], off
	global_load_dwordx4 v[214:217], v[54:55], off offset:64
	global_load_dwordx4 v[218:221], v[56:57], off offset:64
	global_load_dwordx4 v[222:225], v[58:59], off offset:64
	global_load_dwordx4 v[226:229], v[60:61], off offset:64
	global_load_dwordx4 v[230:233], v[62:63], off offset:64
	global_load_dwordx4 v[234:237], v[64:65], off offset:64
	global_load_dwordx4 v[238:241], v[156:157], off offset:64
	global_load_dwordx4 v[242:245], v[158:159], off offset:64
	s_add_u32 s12, s12, 0x80
	s_addc_u32 s13, s13, 0
	s_add_i32 s1, s1, 64
	s_waitcnt vmcnt(33)
	v_mfma_f32_16x16x32_bf16 v[16:19], v[82:85], v[92:95], v[16:19]
	s_waitcnt vmcnt(32)
	v_mfma_f32_16x16x32_bf16 v[20:23], v[82:85], v[96:99], v[20:23]
	s_waitcnt vmcnt(31)
	v_mfma_f32_16x16x32_bf16 v[12:15], v[82:85], v[100:103], v[12:15]
	s_waitcnt vmcnt(30)
	v_mfma_f32_16x16x32_bf16 v[8:11], v[82:85], v[104:107], v[8:11]
	s_waitcnt vmcnt(29)
	v_mfma_f32_16x16x32_bf16 v[24:27], v[82:85], v[108:111], v[24:27]
	s_waitcnt vmcnt(28)
	v_mfma_f32_16x16x32_bf16 v[28:31], v[82:85], v[112:115], v[28:31]
	s_waitcnt vmcnt(27)
	v_mfma_f32_16x16x32_bf16 v[0:3], v[82:85], v[116:119], v[0:3]
	s_waitcnt vmcnt(26)
	v_mfma_f32_16x16x32_bf16 v[4:7], v[82:85], v[120:123], v[4:7]
	s_waitcnt vmcnt(25)
	v_mfma_f32_16x16x32_bf16 v[16:19], v[86:89], v[124:127], v[16:19]
	s_waitcnt vmcnt(24)
	v_mfma_f32_16x16x32_bf16 v[20:23], v[86:89], v[128:131], v[20:23]
	s_waitcnt vmcnt(23)
	v_mfma_f32_16x16x32_bf16 v[12:15], v[86:89], v[132:135], v[12:15]
	s_waitcnt vmcnt(22)
	v_mfma_f32_16x16x32_bf16 v[8:11], v[86:89], v[136:139], v[8:11]
	s_waitcnt vmcnt(21)
	v_mfma_f32_16x16x32_bf16 v[24:27], v[86:89], v[140:143], v[24:27]
	s_waitcnt vmcnt(20)
	v_mfma_f32_16x16x32_bf16 v[28:31], v[86:89], v[144:147], v[28:31]
	s_waitcnt vmcnt(19)
	v_mfma_f32_16x16x32_bf16 v[0:3], v[86:89], v[148:151], v[0:3]
	s_waitcnt vmcnt(18)
	v_mfma_f32_16x16x32_bf16 v[4:7], v[86:89], v[152:155], v[4:7]
	s_waitcnt vmcnt(15)
	v_mfma_f32_16x16x32_bf16 v[16:19], v[162:165], v[172:175], v[16:19]
	s_waitcnt vmcnt(14)
	v_mfma_f32_16x16x32_bf16 v[20:23], v[162:165], v[176:179], v[20:23]
	s_waitcnt vmcnt(13)
	v_mfma_f32_16x16x32_bf16 v[12:15], v[162:165], v[180:183], v[12:15]
	s_waitcnt vmcnt(12)
	v_mfma_f32_16x16x32_bf16 v[8:11], v[162:165], v[184:187], v[8:11]
	s_waitcnt vmcnt(11)
	v_mfma_f32_16x16x32_bf16 v[24:27], v[162:165], v[188:191], v[24:27]
	s_waitcnt vmcnt(10)
	v_mfma_f32_16x16x32_bf16 v[28:31], v[162:165], v[192:195], v[28:31]
	s_waitcnt vmcnt(9)
	v_mfma_f32_16x16x32_bf16 v[0:3], v[162:165], v[196:199], v[0:3]
	s_waitcnt vmcnt(8)
	v_mfma_f32_16x16x32_bf16 v[4:7], v[162:165], v[210:213], v[4:7]
	s_waitcnt vmcnt(7)
	v_mfma_f32_16x16x32_bf16 v[16:19], v[168:171], v[214:217], v[16:19]
	s_waitcnt vmcnt(6)
	v_mfma_f32_16x16x32_bf16 v[20:23], v[168:171], v[218:221], v[20:23]
	s_waitcnt vmcnt(5)
	v_mfma_f32_16x16x32_bf16 v[12:15], v[168:171], v[222:225], v[12:15]
	s_waitcnt vmcnt(4)
	v_mfma_f32_16x16x32_bf16 v[8:11], v[168:171], v[226:229], v[8:11]
	s_waitcnt vmcnt(3)
	v_mfma_f32_16x16x32_bf16 v[24:27], v[168:171], v[230:233], v[24:27]
	s_waitcnt vmcnt(2)
	v_mfma_f32_16x16x32_bf16 v[28:31], v[168:171], v[234:237], v[28:31]
	s_waitcnt vmcnt(1)
	v_mfma_f32_16x16x32_bf16 v[0:3], v[168:171], v[238:241], v[0:3]
	s_waitcnt vmcnt(0)
	v_mfma_f32_16x16x32_bf16 v[4:7], v[168:171], v[242:245], v[4:7]
	s_cmpk_eq_i32 s12, 0x400
	v_add_u32_e32 v46, 0x4000, v78
	s_and_b32 s12, s14, 0xffffff80
	s_waitcnt lgkmcnt(0)
	s_barrier
; DI void prep_phase(const int wv, const Params& p, int l, LAS unsigned char* lds) {
;     ...
;             __syncthreads();
; #pragma unroll
;             for (int nt = 0; nt < 8; ++nt)
; #pragma unroll
;                 for (int i = 0; i < 4; ++i) part[(wave * 16 + 4 * kq + i) * 128 + 16 * nt + r16] = acc[nt][i];
;             __syncthreads();
;             { const int row = tid >> 5, n4 = (tid & 31) * 4; f32x4 s = *(const f32x4*)(bias1 + kv * 128 + n4);
; #pragma unroll
;               for (int w = 0; w < 8; ++w) s += *(const LAS f32x4*)(part + (w * 16 + row) * 128 + n4);
;               u32x2 hv; hv.x = pk2(silu_f(s.x), silu_f(s.y)); hv.y = pk2(silu_f(s.z), silu_f(s.w));
;               *(LAS u32x2*)(Hs + row * 136 + n4) = hv; }
;             __syncthreads();
;             f32x4 acc2 = {0.f, 0.f, 0.f, 0.f};
; #pragma unroll
;             for (int ks = 0; ks < 4; ++ks) {
;                 const bf16x8 a = *(const LAS bf16x8*)(Hs + r16 * 136 + ks * 32 + 8 * kq);
;                 const bf16x8 bb = *(const bf16x8*)(W2t + (size_t)(16 * wave + r16) * 128 + ks * 32 + 8 * kq);
;                 acc2 = __builtin_amdgcn_mfma_f32_16x16x32_bf16(a, bb, acc2, 0, 0, 0);
;             }
;             const int n = 16 * wave + r16;
;             if (kv == 0) {
;                 float ss[4];
; #pragma unroll
;                 for (int i = 0; i < 4; ++i) { float s = acc2[i] * acc2[i]; s += __shfl_xor(s, 1); s += __shfl_xor(s, 2); s += __shfl_xor(s, 4); s += __shfl_xor(s, 8); ss[i] = s; }
;                 if (r16 == 0) {
; #pragma unroll
;                     for (int i = 0; i < 4; ++i) red[wave * 16 + 4 * kq + i] = ss[i]; }
;                 __syncthreads();
;                 const float gn = p.k_gain[(l * 3 + 0) * 128 + n];
; #pragma unroll
;                 for (int i = 0; i < 4; ++i) { const int row = 4 * kq + i; float s = 0.f;
; #pragma unroll
;                     for (int w = 0; w < 8; ++w) s += red[w * 16 + row];
;                     const float rstd = rsqrtf(s * (1.f / 128.f) + 1e-6f); const int c = c0 + row;
;                     const float v = (c < 255) ? acc2[i] * rstd * gn : 0.f;
;                     kcmp[(((size_t)b * 2 + g) * 256 + c) * 128 + n] = (bf16_t)(pk2(v, 0.f) & 0xffffu); }
;             } else {
;                 float v[4];
; #pragma unroll
;                 for (int i = 0; i < 4; ++i) v[i] = (c0 + 4 * kq + i < 255) ? acc2[i] : 0.f;
	ds_write2_b32 v46, v16, v20 offset1:16
	ds_write2_b32 v46, v17, v21 offset0:128 offset1:144
	v_add_u32_e32 v16, 0x4400, v78
	s_ashr_i32 s13, s12, 31
	ds_write2_b32 v16, v18, v22 offset1:16
	ds_write2_b32 v16, v19, v23 offset0:128 offset1:144
	ds_write2_b32 v46, v12, v8 offset0:32 offset1:48
	ds_write2_b32 v46, v13, v9 offset0:160 offset1:176
	ds_write2_b32 v16, v14, v10 offset0:32 offset1:48
	ds_write2_b32 v16, v15, v11 offset0:160 offset1:176
	ds_write2_b32 v46, v24, v28 offset0:64 offset1:80
	ds_write2_b32 v46, v25, v29 offset0:192 offset1:208
	ds_write2_b32 v16, v26, v30 offset0:64 offset1:80
	ds_write2_b32 v16, v27, v31 offset0:192 offset1:208
	ds_write2_b32 v46, v0, v4 offset0:96 offset1:112
	ds_write2_b32 v46, v1, v5 offset0:224 offset1:240
	ds_write2_b32 v16, v2, v6 offset0:96 offset1:112
	ds_write2_b32 v16, v3, v7 offset0:224 offset1:240
	v_lshl_add_u64 v[0:1], s[12:13], 2, v[34:35]
	s_waitcnt lgkmcnt(0)
	s_barrier
	global_load_dwordx4 v[0:3], v[0:1], off
	ds_read_b128 v[4:7], v70 offset:16384
	s_lshl_b64 s[10:11], s[10:11], 15
	v_lshl_add_u64 v[12:13], v[38:39], 0, s[10:11]
	s_mov_b64 s[10:11], -1
	s_and_b64 vcc, exec, s[8:9]
	s_waitcnt vmcnt(0) lgkmcnt(0)
	v_pk_add_f32 v[6:7], v[2:3], v[6:7]
	v_pk_add_f32 v[4:5], v[0:1], v[4:5]
	ds_read_b128 v[0:3], v70 offset:24576
	s_waitcnt lgkmcnt(0)
	v_pk_add_f32 v[6:7], v[6:7], v[2:3]
	v_pk_add_f32 v[4:5], v[4:5], v[0:1]
	ds_read_b128 v[0:3], v70 offset:32768
	s_waitcnt lgkmcnt(0)
	v_pk_add_f32 v[6:7], v[6:7], v[2:3]
	v_pk_add_f32 v[4:5], v[4:5], v[0:1]
	ds_read_b128 v[0:3], v70 offset:40960
	s_waitcnt lgkmcnt(0)
	v_pk_add_f32 v[6:7], v[6:7], v[2:3]
	v_pk_add_f32 v[4:5], v[4:5], v[0:1]
	ds_read_b128 v[0:3], v70 offset:49152
	s_waitcnt lgkmcnt(0)
	v_pk_add_f32 v[6:7], v[6:7], v[2:3]
	v_pk_add_f32 v[4:5], v[4:5], v[0:1]
	ds_read_b128 v[0:3], v70 offset:57344
	s_waitcnt lgkmcnt(0)
	v_pk_add_f32 v[6:7], v[6:7], v[2:3]
	v_pk_add_f32 v[4:5], v[4:5], v[0:1]
	ds_read_b128 v[0:3], v71 offset:49152
	s_waitcnt lgkmcnt(0)
	v_pk_add_f32 v[6:7], v[6:7], v[2:3]
	v_pk_add_f32 v[4:5], v[4:5], v[0:1]
	ds_read_b128 v[0:3], v71 offset:57344
	s_waitcnt lgkmcnt(0)
	v_pk_add_f32 v[0:1], v[4:5], v[0:1]
	s_nop 0
	v_mul_f32_e32 v4, 0xbfb8aa3b, v0
	v_mul_f32_e32 v5, 0xbfb8aa3b, v1
	v_exp_f32_e32 v4, v4
	v_exp_f32_e32 v5, v5
	v_pk_add_f32 v[2:3], v[6:7], v[2:3]
	v_add_f32_e32 v4, 1.0, v4
	v_add_f32_e32 v5, 1.0, v5
	v_rcp_f32_e32 v4, v4
	v_rcp_f32_e32 v5, v5
	s_nop 0
	v_pk_mul_f32 v[0:1], v[0:1], v[4:5]
	s_nop 0
	v_cvt_pk_bf16_f32 v0, v0, v1
	v_mul_f32_e32 v1, 0xbfb8aa3b, v2
	v_exp_f32_e32 v1, v1
	s_nop 0
	v_add_f32_e32 v1, 1.0, v1
	v_rcp_f32_e32 v4, v1
	v_mul_f32_e32 v1, 0xbfb8aa3b, v3
	v_exp_f32_e32 v1, v1
	s_nop 0
	v_add_f32_e32 v1, 1.0, v1
	v_rcp_f32_e32 v5, v1
	s_nop 0
	v_pk_mul_f32 v[2:3], v[2:3], v[4:5]
	s_nop 0
	v_cvt_pk_bf16_f32 v1, v2, v3
	ds_write_b64 v72, v[0:1]
	s_waitcnt lgkmcnt(0)
	s_barrier
	global_load_dwordx4 v[4:7], v[12:13], off
	global_load_dwordx4 v[8:11], v[12:13], off offset:64
	ds_read_b128 v[0:3], v73
	s_waitcnt vmcnt(1) lgkmcnt(0)
	v_mfma_f32_16x16x32_bf16 v[0:3], v[0:3], v[4:7], 0
	ds_read_b128 v[4:7], v73 offset:64
	s_waitcnt vmcnt(0) lgkmcnt(0)
	v_mfma_f32_16x16x32_bf16 v[0:3], v[4:7], v[8:11], v[0:3]
	global_load_dwordx4 v[8:11], v[12:13], off offset:128
	ds_read_b128 v[4:7], v73 offset:128
	s_waitcnt vmcnt(0) lgkmcnt(0)
	v_mfma_f32_16x16x32_bf16 v[0:3], v[4:7], v[8:11], v[0:3]
	global_load_dwordx4 v[8:11], v[12:13], off offset:192
	ds_read_b128 v[4:7], v73 offset:192
	v_or_b32_e32 v12, s15, v32
	s_waitcnt vmcnt(0) lgkmcnt(0)
	v_mfma_f32_16x16x32_bf16 v[0:3], v[4:7], v[8:11], v[0:3]
	s_cbranch_vccz .LBB0_365
	s_movk_i32 s1, 0xfc
	v_cmp_ne_u32_e32 vcc, s1, v12
	v_lshl_add_u64 v[6:7], s[6:7], 0, v[36:37]
	s_lshl_b32 s1, s16, 17
	v_readlane_b32 s6, v253, 63
	s_add_u32 s6, s6, s1
	v_readlane_b32 s1, v254, 0
	v_lshlrev_b64 v[6:7], 9, v[6:7]
	s_addc_u32 s7, s1, 0
	v_lshl_add_u64 v[6:7], s[6:7], 0, v[6:7]
	s_lshl_b32 s86, s15, 1
	v_cndmask_b32_e32 v5, 0, v3, vcc
	v_lshl_add_u64 v[6:7], v[6:7], 0, s[86:87]
	v_lshlrev_b32_e32 v8, 1, v32
	v_mov_b32_e32 v9, v161
	v_cvt_pk_bf16_f32 v4, v0, v1
	v_cvt_pk_bf16_f32 v5, v2, v5
	v_lshl_add_u64 v[6:7], v[6:7], 0, v[8:9]
	global_store_dwordx2 v[6:7], v[4:5], off
	s_cbranch_execnz .LBB0_360
	s_branch .LBB0_366

; DI unsigned pk2(float lo, float hi) { f32x2 v = {lo, hi}; bf16x2n b = __builtin_convertvector(v, bf16x2n); return __builtin_bit_cast(unsigned, b); }
; DI float sigmoid_f(float x) { return fast_rcp(1.f + fast_exp2(-1.44269504f * x)); }
; #define ATT_GL(k) bf2f(Vt[(unsigned)(VR_GL + head * 3 + (k)) * (unsigned)M + m])
; DI void unit(const int wv, const Params& p, int l, int b, int g, int qt, LAS unsigned char* lds) {
;     ...
;     { const float gt = sigmoid_f(ATT_GL(0));
; #pragma unroll
;       for (int dt = 0; dt < 4; ++dt)
; #pragma unroll
;           for (int i = 0; i < 8; ++i) outp[(dt * 8 + i) * 64] = pk2(gt * O[dt][2 * i], gt * O[dt][2 * i + 1]); }
;     __syncthreads();
;     unsigned long long wuni = 0ull, wall = ~0ull;
;     {
;         for (int t8 = 0; t8 < 8; ++t8) {
;             const float v = imp[(8 * wave + t8) * 64 + lane];
;             const bool valid = lane <= qt, forced = (lane == 0) || (lane == qt) || (lane == qt - 1);
;             const float sc = valid ? (v + (forced ? 1000.f : 0.f)) : -1e30f;
;             int rank = 0;
; #pragma unroll 4
;             for (int jj = 0; jj <= qt; ++jj) {        const float sj = __builtin_bit_cast(float, __builtin_amdgcn_readlane(__builtin_bit_cast(int, sc), jj)); rank += ((sj > sc) || (sj == sc && jj < lane)) ? 1 : 0; }
;             const unsigned long long sel = __ballot((rank < 16) && valid);
;             if (lane == 0) selw[8 * wave + t8] = sel;
.LBB0_544:
	v_mul_u32_u24_e32 v222, 0xc000, v194
	s_mov_b32 s0, 0x800000
	v_add3_u32 v160, v212, v222, s0
	v_lshl_add_u64 v[64:65], v[160:161], 1, s[82:83]
	s_barrier
	global_load_ushort v64, v[64:65], off
	v_lshlrev_b32_e32 v65, 13, v191
	v_lshlrev_b32_e32 v66, 2, v193
	v_readlane_b32 s0, v254, 36
	v_cmp_eq_u32_e32 vcc, 0, v193
	s_add_i32 s22, s85, 1
	v_add3_u32 v221, s0, v65, v66
	v_readlane_b32 s0, v254, 35
	s_mov_b32 s6, 0
	s_waitcnt vmcnt(0)
	v_lshlrev_b32_e32 v64, 16, v64
	v_mul_f32_e32 v64, 0xbfb8aa3b, v64
	v_exp_f32_e32 v64, v64
	s_nop 0
	v_add_f32_e32 v64, 1.0, v64
	v_rcp_f32_e32 v64, v64
	s_nop 0
	v_pk_mul_f32 v[48:49], v[48:49], v[64:65] op_sel_hi:[1,0]
	v_pk_mul_f32 v[50:51], v[50:51], v[64:65] op_sel_hi:[1,0]
	v_pk_mul_f32 v[0:1], v[0:1], v[64:65] op_sel_hi:[1,0]
	v_pk_mul_f32 v[52:53], v[52:53], v[64:65] op_sel_hi:[1,0]
	v_pk_mul_f32 v[54:55], v[54:55], v[64:65] op_sel_hi:[1,0]
	v_pk_mul_f32 v[56:57], v[56:57], v[64:65] op_sel_hi:[1,0]
	v_pk_mul_f32 v[58:59], v[58:59], v[64:65] op_sel_hi:[1,0]
	v_pk_mul_f32 v[60:61], v[60:61], v[64:65] op_sel_hi:[1,0]
	v_pk_mul_f32 v[62:63], v[62:63], v[64:65] op_sel_hi:[1,0]
	v_pk_mul_f32 v[32:33], v[32:33], v[64:65] op_sel_hi:[1,0]
	v_pk_mul_f32 v[34:35], v[34:35], v[64:65] op_sel_hi:[1,0]
	v_pk_mul_f32 v[36:37], v[36:37], v[64:65] op_sel_hi:[1,0]
	v_pk_mul_f32 v[38:39], v[38:39], v[64:65] op_sel_hi:[1,0]
	v_pk_mul_f32 v[40:41], v[40:41], v[64:65] op_sel_hi:[1,0]
	v_pk_mul_f32 v[42:43], v[42:43], v[64:65] op_sel_hi:[1,0]
	v_pk_mul_f32 v[44:45], v[44:45], v[64:65] op_sel_hi:[1,0]
	v_pk_mul_f32 v[46:47], v[46:47], v[64:65] op_sel_hi:[1,0]
	v_pk_mul_f32 v[16:17], v[16:17], v[64:65] op_sel_hi:[1,0]
	v_pk_mul_f32 v[18:19], v[18:19], v[64:65] op_sel_hi:[1,0]
	v_pk_mul_f32 v[20:21], v[20:21], v[64:65] op_sel_hi:[1,0]
	v_pk_mul_f32 v[22:23], v[22:23], v[64:65] op_sel_hi:[1,0]
	v_pk_mul_f32 v[24:25], v[24:25], v[64:65] op_sel_hi:[1,0]
	v_pk_mul_f32 v[26:27], v[26:27], v[64:65] op_sel_hi:[1,0]
	v_pk_mul_f32 v[28:29], v[28:29], v[64:65] op_sel_hi:[1,0]
	v_pk_mul_f32 v[30:31], v[30:31], v[64:65] op_sel_hi:[1,0]
	v_pk_mul_f32 v[2:3], v[2:3], v[64:65] op_sel_hi:[1,0]
	v_pk_mul_f32 v[4:5], v[4:5], v[64:65] op_sel_hi:[1,0]
	v_pk_mul_f32 v[6:7], v[6:7], v[64:65] op_sel_hi:[1,0]
	v_pk_mul_f32 v[8:9], v[8:9], v[64:65] op_sel_hi:[1,0]
	v_pk_mul_f32 v[10:11], v[10:11], v[64:65] op_sel_hi:[1,0]
	v_pk_mul_f32 v[12:13], v[12:13], v[64:65] op_sel_hi:[1,0]
	v_pk_mul_f32 v[14:15], v[14:15], v[64:65] op_sel_hi:[1,0]
	v_cvt_pk_bf16_f32 v48, v48, v49
	v_cvt_pk_bf16_f32 v49, v50, v51
	v_cvt_pk_bf16_f32 v0, v0, v1
	v_cvt_pk_bf16_f32 v50, v52, v53
	v_cvt_pk_bf16_f32 v51, v54, v55
	v_cvt_pk_bf16_f32 v52, v56, v57
	v_cvt_pk_bf16_f32 v53, v58, v59
	v_cvt_pk_bf16_f32 v54, v60, v61
	v_cvt_pk_bf16_f32 v55, v62, v63
	v_cvt_pk_bf16_f32 v32, v32, v33
	v_cvt_pk_bf16_f32 v33, v34, v35
	v_cvt_pk_bf16_f32 v34, v36, v37
	v_cvt_pk_bf16_f32 v35, v38, v39
	v_cvt_pk_bf16_f32 v36, v40, v41
	v_cvt_pk_bf16_f32 v37, v42, v43
	v_cvt_pk_bf16_f32 v38, v44, v45
	v_cvt_pk_bf16_f32 v39, v46, v47
	v_cvt_pk_bf16_f32 v16, v16, v17
	v_cvt_pk_bf16_f32 v17, v18, v19
	v_cvt_pk_bf16_f32 v18, v20, v21
	v_cvt_pk_bf16_f32 v19, v22, v23
	v_cvt_pk_bf16_f32 v20, v24, v25
	v_cvt_pk_bf16_f32 v21, v26, v27
	v_cvt_pk_bf16_f32 v22, v28, v29
	v_cvt_pk_bf16_f32 v23, v30, v31
	v_cvt_pk_bf16_f32 v1, v2, v3
	v_cvt_pk_bf16_f32 v2, v4, v5
	v_cvt_pk_bf16_f32 v3, v6, v7
	v_cvt_pk_bf16_f32 v4, v8, v9
	v_cvt_pk_bf16_f32 v5, v10, v11
	v_cvt_pk_bf16_f32 v6, v12, v13
	v_cvt_pk_bf16_f32 v7, v14, v15
	ds_write2st64_b32 v221, v48, v49 offset1:1
	ds_write2st64_b32 v221, v50, v51 offset0:2 offset1:3
	ds_write2st64_b32 v221, v52, v53 offset0:4 offset1:5
	ds_write2st64_b32 v221, v54, v55 offset0:6 offset1:7
	ds_write2st64_b32 v221, v32, v33 offset0:8 offset1:9
	ds_write2st64_b32 v221, v34, v35 offset0:10 offset1:11
	ds_write2st64_b32 v221, v36, v37 offset0:12 offset1:13
	ds_write2st64_b32 v221, v38, v39 offset0:14 offset1:15
	ds_write2st64_b32 v221, v16, v17 offset0:16 offset1:17
	ds_write2st64_b32 v221, v18, v19 offset0:18 offset1:19
	ds_write2st64_b32 v221, v20, v21 offset0:20 offset1:21
	ds_write2st64_b32 v221, v22, v23 offset0:22 offset1:23
	ds_write2st64_b32 v221, v0, v1 offset0:24 offset1:25
	ds_write2st64_b32 v221, v2, v3 offset0:26 offset1:27
	ds_write2st64_b32 v221, v4, v5 offset0:28 offset1:29
	ds_write2st64_b32 v221, v6, v7 offset0:30 offset1:31
	v_add_u32_e32 v0, s0, v66
	v_lshl_add_u32 v1, v191, 11, v0
	s_waitcnt lgkmcnt(0)
	s_barrier
	v_cmp_eq_u32_e64 s[0:1], s85, v193
	ds_read_b32 v3, v1
	s_or_b64 s[2:3], vcc, s[0:1]
	s_sub_i32 s0, 62, s76
	v_cmp_eq_u32_e64 s[0:1], s0, v193
	s_or_b64 s[0:1], s[2:3], s[0:1]
	v_mov_b32_e32 v1, 0x447a0000
	v_cndmask_b32_e64 v1, 0, v1, s[0:1]
	s_waitcnt lgkmcnt(0)
	v_add_f32_e32 v3, v1, v3
	v_cmp_ge_u32_e64 s[2:3], s85, v193
	v_mov_b32_e32 v2, 0
	s_nop 0
	v_cndmask_b32_e64 v3, v209, v3, s[2:3]
	v_sub_u32_e32 v238, 63, v193
	v_mov_b32_e32 v239, v3
	s_nop 0
.LBB0_545:
	v_readlane_b32 s9, v3, s6
	s_sub_i32 s8, 63, s6
	s_add_i32 s6, s6, 1
	s_cmp_eq_u32 s22, s6
	v_cmp_gt_u64_e64 s[0:1], s[8:9], v[238:239]
	s_nop 1
	v_addc_co_u32_e64 v2, s[0:1], 0, v2, s[0:1]
	s_cbranch_scc0 .LBB0_545
	v_cmp_gt_u32_e64 s[0:1], 16, v2
	s_and_b64 s[0:1], s[0:1], s[2:3]
	s_nop 0
	v_cndmask_b32_e64 v2, 0, 1, s[0:1]
	v_cmp_ne_u32_e64 s[6:7], 0, v2
	s_and_saveexec_b64 s[0:1], vcc
	v_lshl_add_u32 v2, v192, 3, 0
	v_add_u32_e32 v2, 0x15000, v2
	v_mov_b64_e32 v[4:5], s[6:7]
	ds_write_b64 v2, v[4:5]
	s_or_b64 exec, exec, s[0:1]
	v_or_b32_e32 v2, 1, v192
	v_lshl_add_u32 v3, v2, 8, v0
	ds_read_b32 v3, v3
	v_mov_b32_e32 v4, 0
	s_mov_b32 s10, 0
	s_waitcnt lgkmcnt(0)
	v_add_f32_e32 v3, v1, v3
	v_cndmask_b32_e64 v3, v209, v3, s[2:3]
	v_sub_u32_e32 v238, 63, v193
	v_mov_b32_e32 v239, v3
	s_nop 0
; DI void unit(const int wv, const Params& p, int l, int b, int g, int qt, LAS unsigned char* lds) {
;     ...
;         for (int t8 = 0; t8 < 8; ++t8) {
;             const float v = imp[(8 * wave + t8) * 64 + lane];
;             const bool valid = lane <= qt, forced = (lane == 0) || (lane == qt) || (lane == qt - 1);
;             const float sc = valid ? (v + (forced ? 1000.f : 0.f)) : -1e30f;
;             int rank = 0;
; #pragma unroll 4
;             for (int jj = 0; jj <= qt; ++jj) {        const float sj = __builtin_bit_cast(float, __builtin_amdgcn_readlane(__builtin_bit_cast(int, sc), jj)); rank += ((sj > sc) || (sj == sc && jj < lane)) ? 1 : 0; }
;             const unsigned long long sel = __ballot((rank < 16) && valid);
;             if (lane == 0) selw[8 * wave + t8] = sel;
.LBB0_549:
	v_readlane_b32 s9, v3, s10
	s_sub_i32 s8, 63, s10
	s_add_i32 s10, s10, 1
	s_cmp_lg_u32 s22, s10
	v_cmp_gt_u64_e64 s[0:1], s[8:9], v[238:239]
	s_nop 1
	v_addc_co_u32_e64 v4, s[0:1], 0, v4, s[0:1]
	s_cbranch_scc1 .LBB0_549
	v_cmp_gt_u32_e64 s[0:1], 16, v4
	s_and_b64 s[0:1], s[0:1], s[2:3]
	s_nop 0
	v_cndmask_b32_e64 v3, 0, 1, s[0:1]
	v_cmp_ne_u32_e64 s[10:11], 0, v3
	s_and_saveexec_b64 s[0:1], vcc
	v_lshl_add_u32 v2, v2, 3, 0
	v_add_u32_e32 v2, 0x15000, v2
	v_mov_b64_e32 v[4:5], s[10:11]
	ds_write_b64 v2, v[4:5]
	s_or_b64 exec, exec, s[0:1]
	v_or_b32_e32 v2, 2, v192
	v_lshl_add_u32 v3, v2, 8, v0
	ds_read_b32 v3, v3
	v_mov_b32_e32 v4, 0
	s_mov_b32 s12, 0
	s_waitcnt lgkmcnt(0)
	v_add_f32_e32 v3, v1, v3
	v_cndmask_b32_e64 v3, v209, v3, s[2:3]
	v_sub_u32_e32 v238, 63, v193
	v_mov_b32_e32 v239, v3
	s_nop 0
.LBB0_553:
	v_readlane_b32 s9, v3, s12
	s_sub_i32 s8, 63, s12
	s_add_i32 s12, s12, 1
	s_cmp_lg_u32 s22, s12
	v_cmp_gt_u64_e64 s[0:1], s[8:9], v[238:239]
	s_nop 1
	v_addc_co_u32_e64 v4, s[0:1], 0, v4, s[0:1]
	s_cbranch_scc1 .LBB0_553
	v_cmp_gt_u32_e64 s[0:1], 16, v4
	s_and_b64 s[0:1], s[0:1], s[2:3]
	s_nop 0
	v_cndmask_b32_e64 v3, 0, 1, s[0:1]
	v_cmp_ne_u32_e64 s[12:13], 0, v3
	s_and_saveexec_b64 s[0:1], vcc
	v_lshl_add_u32 v2, v2, 3, 0
	v_add_u32_e32 v2, 0x15000, v2
	v_mov_b64_e32 v[4:5], s[12:13]
	ds_write_b64 v2, v[4:5]
	s_or_b64 exec, exec, s[0:1]
	v_or_b32_e32 v2, 3, v192
	v_lshl_add_u32 v3, v2, 8, v0
	ds_read_b32 v3, v3
	v_mov_b32_e32 v4, 0
	s_mov_b32 s14, 0
	s_waitcnt lgkmcnt(0)
	v_add_f32_e32 v3, v1, v3
	v_cndmask_b32_e64 v3, v209, v3, s[2:3]
	v_sub_u32_e32 v238, 63, v193
	v_mov_b32_e32 v239, v3
	s_nop 0
.LBB0_557:
	v_readlane_b32 s9, v3, s14
	s_sub_i32 s8, 63, s14
	s_add_i32 s14, s14, 1
	s_cmp_lg_u32 s22, s14
	v_cmp_gt_u64_e64 s[0:1], s[8:9], v[238:239]
	s_nop 1
	v_addc_co_u32_e64 v4, s[0:1], 0, v4, s[0:1]
	s_cbranch_scc1 .LBB0_557
	v_cmp_gt_u32_e64 s[0:1], 16, v4
	s_and_b64 s[0:1], s[0:1], s[2:3]
	s_nop 0
	v_cndmask_b32_e64 v3, 0, 1, s[0:1]
	v_cmp_ne_u32_e64 s[14:15], 0, v3
	s_and_saveexec_b64 s[0:1], vcc
	v_lshl_add_u32 v2, v2, 3, 0
	v_add_u32_e32 v2, 0x15000, v2
	v_mov_b64_e32 v[4:5], s[14:15]
	ds_write_b64 v2, v[4:5]
	s_or_b64 exec, exec, s[0:1]
	v_or_b32_e32 v2, 4, v192
	v_lshl_add_u32 v3, v2, 8, v0
	ds_read_b32 v3, v3
	v_mov_b32_e32 v4, 0
	s_mov_b32 s16, 0
	s_waitcnt lgkmcnt(0)
	v_add_f32_e32 v3, v1, v3
	v_cndmask_b32_e64 v3, v209, v3, s[2:3]
	v_sub_u32_e32 v238, 63, v193
	v_mov_b32_e32 v239, v3
	s_nop 0
.LBB0_561:
	v_readlane_b32 s9, v3, s16
	s_sub_i32 s8, 63, s16
	s_add_i32 s16, s16, 1
	s_cmp_lg_u32 s22, s16
	v_cmp_gt_u64_e64 s[0:1], s[8:9], v[238:239]
	s_nop 1
	v_addc_co_u32_e64 v4, s[0:1], 0, v4, s[0:1]
	s_cbranch_scc1 .LBB0_561
	v_cmp_gt_u32_e64 s[0:1], 16, v4
	s_and_b64 s[0:1], s[0:1], s[2:3]
	s_nop 0
	v_cndmask_b32_e64 v3, 0, 1, s[0:1]
	v_cmp_ne_u32_e64 s[16:17], 0, v3
	s_and_saveexec_b64 s[0:1], vcc
	v_lshl_add_u32 v2, v2, 3, 0
	v_add_u32_e32 v2, 0x15000, v2
	v_mov_b64_e32 v[4:5], s[16:17]
	ds_write_b64 v2, v[4:5]
	s_or_b64 exec, exec, s[0:1]
	v_or_b32_e32 v2, 5, v192
	v_lshl_add_u32 v3, v2, 8, v0
	ds_read_b32 v3, v3
	v_mov_b32_e32 v4, 0
	s_mov_b32 s18, 0
	s_waitcnt lgkmcnt(0)
	v_add_f32_e32 v3, v1, v3
	v_cndmask_b32_e64 v3, v209, v3, s[2:3]
	v_sub_u32_e32 v238, 63, v193
	v_mov_b32_e32 v239, v3
	s_nop 0
.LBB0_565:
	v_readlane_b32 s9, v3, s18
	s_sub_i32 s8, 63, s18
	s_add_i32 s18, s18, 1
	s_cmp_lg_u32 s22, s18
	v_cmp_gt_u64_e64 s[0:1], s[8:9], v[238:239]
	s_nop 1
	v_addc_co_u32_e64 v4, s[0:1], 0, v4, s[0:1]
	s_cbranch_scc1 .LBB0_565
	v_cmp_gt_u32_e64 s[0:1], 16, v4
	s_and_b64 s[0:1], s[0:1], s[2:3]
	s_nop 0
	v_cndmask_b32_e64 v3, 0, 1, s[0:1]
	v_cmp_ne_u32_e64 s[18:19], 0, v3
	s_and_saveexec_b64 s[0:1], vcc
	v_lshl_add_u32 v2, v2, 3, 0
	v_add_u32_e32 v2, 0x15000, v2
	v_mov_b64_e32 v[4:5], s[18:19]
	ds_write_b64 v2, v[4:5]
	s_or_b64 exec, exec, s[0:1]
	v_or_b32_e32 v2, 6, v192
	v_lshl_add_u32 v3, v2, 8, v0
	ds_read_b32 v3, v3
	v_mov_b32_e32 v4, 0
	s_mov_b32 s20, 0
	s_waitcnt lgkmcnt(0)
	v_add_f32_e32 v3, v1, v3
	v_cndmask_b32_e64 v3, v209, v3, s[2:3]
	v_sub_u32_e32 v238, 63, v193
	v_mov_b32_e32 v239, v3
	s_nop 0
.LBB0_569:
	v_readlane_b32 s9, v3, s20
	s_sub_i32 s8, 63, s20
	s_add_i32 s20, s20, 1
	s_cmp_lg_u32 s22, s20
	v_cmp_gt_u64_e64 s[0:1], s[8:9], v[238:239]
	s_nop 1
	v_addc_co_u32_e64 v4, s[0:1], 0, v4, s[0:1]
	s_cbranch_scc1 .LBB0_569
	v_cmp_gt_u32_e64 s[0:1], 16, v4
	s_and_b64 s[0:1], s[0:1], s[2:3]
	s_nop 0
	v_cndmask_b32_e64 v3, 0, 1, s[0:1]
	v_cmp_ne_u32_e64 s[20:21], 0, v3
	s_and_saveexec_b64 s[0:1], vcc
	v_lshl_add_u32 v2, v2, 3, 0
	v_add_u32_e32 v2, 0x15000, v2
	v_mov_b64_e32 v[4:5], s[20:21]
	ds_write_b64 v2, v[4:5]
	s_or_b64 exec, exec, s[0:1]
	v_or_b32_e32 v2, 7, v192
	v_lshl_add_u32 v0, v2, 8, v0
	ds_read_b32 v0, v0
	s_mov_b32 s23, 0
	s_waitcnt lgkmcnt(0)
	v_add_f32_e32 v0, v1, v0
	v_cndmask_b32_e64 v0, v209, v0, s[2:3]
	v_mov_b32_e32 v1, 0
	v_sub_u32_e32 v238, 63, v193
	v_mov_b32_e32 v239, v0
	s_nop 0
; DI void unit(const int wv, const Params& p, int l, int b, int g, int qt, LAS unsigned char* lds) {
;     ...
;         for (int t8 = 0; t8 < 8; ++t8) {
;             const float v = imp[(8 * wave + t8) * 64 + lane];
;             const bool valid = lane <= qt, forced = (lane == 0) || (lane == qt) || (lane == qt - 1);
;             const float sc = valid ? (v + (forced ? 1000.f : 0.f)) : -1e30f;
;             int rank = 0;
; #pragma unroll 4
;             for (int jj = 0; jj <= qt; ++jj) {        const float sj = __builtin_bit_cast(float, __builtin_amdgcn_readlane(__builtin_bit_cast(int, sc), jj)); rank += ((sj > sc) || (sj == sc && jj < lane)) ? 1 : 0; }
;             const unsigned long long sel = __ballot((rank < 16) && valid);
;             if (lane == 0) selw[8 * wave + t8] = sel;
;             wuni |= sel; wall &= sel;
;         }
;         if (lane == 0) uniw[wave] = wuni;
;     }
;     __syncthreads();
.LBB0_573:
	v_readlane_b32 s9, v0, s23
	s_sub_i32 s8, 63, s23
	s_add_i32 s23, s23, 1
	s_cmp_lg_u32 s22, s23
	v_cmp_gt_u64_e64 s[0:1], s[8:9], v[238:239]
	s_nop 1
	v_addc_co_u32_e64 v1, s[0:1], 0, v1, s[0:1]
	s_cbranch_scc1 .LBB0_573
	v_cmp_gt_u32_e64 s[0:1], 16, v1
	s_and_b64 s[0:1], s[0:1], s[2:3]
	s_nop 0
	v_cndmask_b32_e64 v0, 0, 1, s[0:1]
	v_cmp_ne_u32_e64 s[0:1], 0, v0
	s_and_saveexec_b64 s[2:3], vcc
	v_lshl_add_u32 v0, v2, 3, 0
	v_add_u32_e32 v0, 0x15000, v0
	v_mov_b64_e32 v[2:3], s[0:1]
	ds_write_b64 v0, v[2:3]
	s_or_b64 exec, exec, s[2:3]
	s_or_b64 s[2:3], s[10:11], s[6:7]
	s_or_b64 s[2:3], s[2:3], s[12:13]
	s_or_b64 s[2:3], s[2:3], s[14:15]
	s_or_b64 s[2:3], s[2:3], s[16:17]
	s_or_b64 s[2:3], s[2:3], s[18:19]
	s_or_b64 s[2:3], s[2:3], s[20:21]
	s_or_b64 s[0:1], s[2:3], s[0:1]
	s_and_saveexec_b64 s[2:3], vcc
	v_lshl_add_u32 v0, v191, 3, 0
	v_add_u32_e32 v0, 0x15200, v0
	v_mov_b64_e32 v[2:3], s[0:1]
	ds_write_b64 v0, v[2:3]
	s_or_b64 exec, exec, s[2:3]
	v_readlane_b32 s2, v254, 37
	s_waitcnt lgkmcnt(0)
	s_barrier
; #define LAS __attribute__((address_space(3)))
; #define ATT_LOAD(j) do { _Pragma("unroll") for (int _i = 0; _i < 2; ++_i) { const int _c = tid + 512 * _i; \
;         kr[_i] = *(const u32x4*)(kbase + (size_t)(64 * (j) + (_c >> 4)) * ldk + (_c & 15) * 16); \
;         if (MODE != 0) vr[_i] = *(const u32x4*)(vbase + (size_t)(_c >> 3) * ldv + (size_t)(j) * 128 + (_c & 7) * 16); } } while (0)
; #define ATT_STORE(LB) do { _Pragma("unroll") for (int _i = 0; _i < 2; ++_i) { const int _c = tid + 512 * _i; \
;         *(LAS u32x4*)((LB) + K_OFF + (_c >> 4) * KST + (_c & 15) * 16) = kr[_i]; \
;         if (MODE != 0) { LAS u32x2* _d = (LAS u32x2*)((LB) + V_OFF + (_c >> 3) * VST + (_c & 7) * 16); _d[0] = (u32x2){vr[_i].x, vr[_i].y}; _d[1] = (u32x2){vr[_i].z, vr[_i].w}; } } } while (0)
; #define ATT_GK(k) wave_max(fmaxf(fabsf(p.k_gain[(l * 3 + (k)) * 128 + lane]), fabsf(p.k_gain[(l * 3 + (k)) * 128 + lane + 64])))
; template <int MODE> ...
;     ...
;     int j = __builtin_ctzll(tiles); tiles &= tiles - 1;
;     LAS unsigned char* const lds0 = lds;
;     ATT_LOAD(j); ATT_STORE(lds0);
;     __syncthreads();
; DI void unit(const int wv, const Params& p, int l, int b, int g, int qt, LAS unsigned char* lds) {
;     ...
;     unsigned long long uni = 0ull;
; #pragma unroll
;     for (int w = 0; w < 8; ++w) uni |= uniw[w];
;     const unsigned long long selm = selw[tok_l];
;     {
;         const char* kb = (const char*)(P + (size_t)b * T * PWID + PC_KS + g * 128);
;         const char* vb = (const char*)(Vt + (size_t)(VR_VS + g * 128) * M + (size_t)b * T);
;         float lr = 0.f;
; #pragma unroll
;         for (int dt = 0; dt < 4; ++dt)
; #pragma unroll
;             for (int i = 0; i < 16; ++i) O[dt][i] = 0.f;
;         branch<2>(wv, lds, qf, kb, (long)PWID * 2, vb, (long)M * 2, uni, wuni, wall, qt, t_tok, sc_l2, sl_l2, qn * ATT_GK(1), selm, 0.f, lr, O, nullptr);
	v_mov_b32_e32 v0, s2
	ds_read_b128 v[0:3], v0
	s_add_i32 s2, 0, 0x15200
	v_mov_b32_e32 v4, s2
	v_readlane_b32 s4, v254, 38
	ds_read_b128 v[4:7], v4
	s_waitcnt lgkmcnt(1)
	v_readfirstlane_b32 s2, v0
	v_mov_b32_e32 v0, s4
	v_readlane_b32 s6, v254, 39
	s_mul_i32 s12, s88, 0x1800000
	ds_read_b128 v[8:11], v0
	v_mov_b32_e32 v0, s6
	s_add_u32 s12, s80, s12
	v_readlane_b32 s14, v255, 10
	v_readfirstlane_b32 s3, v1
	v_readfirstlane_b32 s5, v3
	v_readfirstlane_b32 s4, v2
	ds_read_b128 v[0:3], v0
	s_addc_u32 s13, s81, 0
	v_readlane_b32 s15, v255, 11
	s_and_b64 s[14:15], s[14:15], exec
	s_cselect_b32 s14, 0x80, 0
	s_lshl_b32 s15, s14, 15
	s_add_u32 s22, s82, s15
	v_readlane_b32 s15, v255, 9
	v_readlane_b32 s36, v253, 0
	s_waitcnt lgkmcnt(0)
	v_readfirstlane_b32 s10, v0
	v_lshl_add_u32 v0, v190, 3, 0
	v_add_u32_e32 v160, s15, v193
	v_readlane_b32 s50, v253, 14
	v_readlane_b32 s51, v253, 15
	v_add_u32_e32 v0, 0x15000, v0
	v_readfirstlane_b32 s7, v9
	v_lshl_add_u64 v[186:187], v[160:161], 2, s[50:51]
	v_readfirstlane_b32 s6, v8
	ds_read_b64 v[188:189], v0
	global_load_dword v8, v[186:187], off offset:512
	global_load_dword v9, v[186:187], off offset:768
	v_readfirstlane_b32 s19, v5
	v_readfirstlane_b32 s18, v4
	v_readfirstlane_b32 s21, v7
	v_readfirstlane_b32 s20, v6
	s_addc_u32 s23, s83, 0
	s_or_b64 s[18:19], s[20:21], s[18:19]
	s_or_b64 s[2:3], s[18:19], s[2:3]
	s_or_b64 s[2:3], s[2:3], s[4:5]
	v_readfirstlane_b32 s9, v11
	v_readfirstlane_b32 s8, v10
	s_or_b64 s[2:3], s[2:3], s[6:7]
	v_readfirstlane_b32 s11, v1
	s_or_b64 s[2:3], s[2:3], s[8:9]
	v_readfirstlane_b32 s17, v3
	v_readfirstlane_b32 s16, v2
	s_or_b64 s[2:3], s[2:3], s[10:11]
	s_mov_b32 s8, -1
	s_or_b64 s[2:3], s[2:3], s[16:17]
	s_lshl_b32 s15, s88, 12
	s_lshl_b32 s4, s14, 1
	s_add_u32 s6, s12, s4
	v_mbcnt_lo_u32_b32 v0, s8, 0
	v_mbcnt_hi_u32_b32 v0, s8, v0
	s_addc_u32 s7, s13, 0
	s_lshl_b32 s4, s88, 13
	v_add_u32_e32 v10, s64, v0
	s_add_u32 s4, s22, s4
	s_addc_u32 s5, s23, 0
	v_lshlrev_b32_e32 v2, 4, v10
	v_and_b32_e32 v160, 0xf0, v2
	s_ff1_i32_b64 s18, s[2:3]
	s_add_u32 s8, s2, -1
	v_lshl_add_u64 v[0:1], s[6:7], 0, v[160:161]
	s_mov_b64 s[6:7], 0x1400
	s_addc_u32 s9, s3, -1
	s_lshl_b32 s10, s18, 6
	v_lshl_add_u64 v[190:191], v[0:1], 0, s[6:7]
	s_lshl_b32 s6, s18, 7
	v_ashrrev_i32_e32 v4, 3, v10
	s_add_u32 s6, s4, s6
	v_ashrrev_i32_e32 v223, 4, v10
	v_ashrrev_i32_e32 v5, 31, v4
	s_addc_u32 s7, s5, 0
	v_and_b32_e32 v192, 0x70, v2
	v_mov_b32_e32 v193, v161
	v_add_u32_e32 v2, s10, v223
	v_lshlrev_b64 v[194:195], 15, v[4:5]
	v_add_u32_e32 v5, 0x200, v10
	v_lshl_add_u64 v[0:1], s[6:7], 0, v[192:193]
	v_mad_i64_i32 v[2:3], s[6:7], v2, s68, v[190:191]
	v_ashrrev_i32_e32 v224, 4, v5
	v_lshl_add_u64 v[6:7], v[0:1], 0, v[194:195]
	global_load_dwordx4 v[144:147], v[2:3], off
	global_load_dwordx4 v[148:151], v[6:7], off
	v_add_u32_e32 v2, s10, v224
	v_mad_i64_i32 v[2:3], s[6:7], v2, s68, v[190:191]
	global_load_dwordx4 v[152:155], v[2:3], off
	v_ashrrev_i32_e32 v2, 3, v5
	v_ashrrev_i32_e32 v3, 31, v2
	v_lshlrev_b64 v[196:197], 15, v[2:3]
	v_lshl_add_u64 v[0:1], v[0:1], 0, v[196:197]
	global_load_dwordx4 v[156:159], v[0:1], off
	s_movk_i32 s6, 0x110
	s_movk_i32 s7, 0x88
	v_mul_lo_u32 v225, v223, s6
	v_add_u32_e32 v5, 0, v160
	v_add_u32_e32 v6, 0, v192
	v_mul_lo_u32 v227, v4, s7
	v_add_u32_e32 v7, v5, v225
	v_mul_lo_u32 v228, v224, s6
	v_mul_lo_u32 v229, v2, s7
	v_bfe_u32 v3, v10, 5, 1
	v_mov_b32_e32 v14, v161
	v_mov_b32_e32 v15, v161
	v_lshlrev_b32_e32 v231, 4, v3
	s_waitcnt vmcnt(5)
	v_max_f32_e64 v1, |v8|, |v8|
	s_waitcnt vmcnt(4)
	v_max_f32_e64 v0, |v9|, |v9|
	v_max_f32_e32 v0, v1, v0
	ds_bpermute_b32 v1, v216, v0
	v_lshlrev_b32_e32 v232, 3, v3
	v_lshlrev_b32_e32 v234, 2, v3
	v_mov_b32_e32 v2, v161
	v_mov_b32_e32 v3, v161
	s_waitcnt lgkmcnt(0)
	v_max_f32_e32 v1, v1, v1
	v_max_f32_e32 v0, v0, v1
	ds_bpermute_b32 v1, v217, v0
	v_mov_b32_e32 v4, v161
	v_mov_b32_e32 v8, v161
	v_mov_b32_e32 v9, v161
	v_mov_b32_e32 v11, v161
	s_waitcnt lgkmcnt(0)
	v_max_f32_e32 v1, v1, v1
	v_max_f32_e32 v0, v0, v1
	ds_bpermute_b32 v1, v218, v0
	v_mov_b32_e32 v12, v161
	v_mov_b32_e32 v13, v161
	s_mov_b32 s16, 0
	s_and_b64 s[2:3], s[8:9], s[2:3]
	s_waitcnt lgkmcnt(0)
	v_max_f32_e32 v1, v1, v1
	v_max_f32_e32 v0, v0, v1
	ds_bpermute_b32 v1, v219, v0
	v_lshl_add_u64 v[198:199], s[4:5], 0, v[192:193]
	v_mov_b32_e32 v193, 0
	v_readlane_b32 s37, v253, 1
	v_readlane_b32 s38, v253, 2
	s_waitcnt lgkmcnt(0)
	v_max_f32_e32 v1, v1, v1
	v_max_f32_e32 v0, v0, v1
	ds_bpermute_b32 v1, v220, v0
	v_readlane_b32 s39, v253, 3
	v_readlane_b32 s40, v253, 4
	v_readlane_b32 s41, v253, 5
	v_readlane_b32 s42, v253, 6
	s_waitcnt lgkmcnt(0)
	v_max_f32_e32 v1, v1, v1
	v_max_f32_e32 v0, v0, v1
	ds_bpermute_b32 v1, v214, v0
	v_readlane_b32 s43, v253, 7
	v_readlane_b32 s44, v253, 8
	v_readlane_b32 s45, v253, 9
	v_readlane_b32 s46, v253, 10
	s_waitcnt lgkmcnt(0)
	v_max_f32_e32 v1, v1, v1
	v_max_f32_e32 v0, v0, v1
	v_mul_f32_e32 v226, v215, v0
	v_add3_u32 v0, v6, v227, s84
	v_mov_b32_e32 v1, v161
	v_readlane_b32 s47, v253, 11
	v_readlane_b32 s48, v253, 12
	v_readlane_b32 s49, v253, 13
	s_waitcnt vmcnt(3)
	ds_write_b128 v7, v[144:147]
	s_waitcnt vmcnt(2)
	ds_write2_b64 v0, v[148:149], v[150:151] offset1:1
	v_add_u32_e32 v0, v5, v228
	v_mov_b32_e32 v5, v161
	v_mov_b32_e32 v7, v161
	s_waitcnt vmcnt(1)
	ds_write_b128 v0, v[152:155]
	v_add3_u32 v0, v6, v229, s84
	v_mov_b32_e32 v6, v161
	s_waitcnt vmcnt(0)
	ds_write2_b64 v0, v[156:157], v[158:159] offset1:1
	v_and_b32_e32 v0, 31, v10
	v_mul_u32_u24_e32 v230, 0x110, v0
	v_mul_u32_u24_e32 v233, 0x88, v0
	v_mov_b32_e32 v0, v161
	v_mov_b32_e32 v10, v161
	v_mov_b64_e32 v[30:31], v[14:15]
	v_mov_b64_e32 v[46:47], v[14:15]
	v_mov_b64_e32 v[62:63], v[14:15]
	v_mov_b64_e32 v[28:29], v[12:13]
	v_mov_b64_e32 v[26:27], v[10:11]
	v_mov_b64_e32 v[24:25], v[8:9]
	v_mov_b64_e32 v[22:23], v[6:7]
	v_mov_b64_e32 v[20:21], v[4:5]
	v_mov_b64_e32 v[18:19], v[2:3]
	v_mov_b64_e32 v[16:17], v[0:1]
	v_mov_b64_e32 v[44:45], v[12:13]
	v_mov_b64_e32 v[42:43], v[10:11]
	v_mov_b64_e32 v[40:41], v[8:9]
	v_mov_b64_e32 v[38:39], v[6:7]
	v_mov_b64_e32 v[36:37], v[4:5]
	v_mov_b64_e32 v[34:35], v[2:3]
	v_mov_b64_e32 v[32:33], v[0:1]
	v_mov_b64_e32 v[60:61], v[12:13]
	v_mov_b64_e32 v[58:59], v[10:11]
	v_mov_b64_e32 v[56:57], v[8:9]
	v_mov_b64_e32 v[54:55], v[6:7]
	v_mov_b64_e32 v[52:53], v[4:5]
	v_mov_b64_e32 v[50:51], v[2:3]
	v_mov_b64_e32 v[48:49], v[0:1]
	s_waitcnt lgkmcnt(0)
	s_barrier
	s_branch .LBB0_581
